# batched residual epilogues for out-proj and both ctx-row GEMMs (loads first, one wait) on top of previous best
# baseline (speedup 1.0000x reference)
; #define MFMA32(a, b, c) __builtin_amdgcn_mfma_f32_32x32x16_bf16((a), (b), (c), 0, 0, 0)
; template <int MF, int BK, class Epi>
; DI void gemm_phase_t(char* lds, const GemmDesc g, const Epi epi) {
;     ...
;     for (int kt = 0; kt < nk; ++kt) {
;       __syncthreads();
;       const u16* sA = sbase + (kt & 1) * STG;
;       const u16* sB = sA + BM * LS;
;       if (kt + 1 < nk) {
;         u16* nA = sbase + ((kt + 1) & 1) * STG;
; #pragma unroll
;         for (int j = 0; j < APT; ++j) *(u32x4*)(nA + (lr + RSTEP * j) * LS + lc * 8) = ra[j];
; #pragma unroll
;         for (int j = 0; j < BPT; ++j) *(u32x4*)(nA + BM * LS + (lr + RSTEP * j) * LS + lc * 8) = rb[j];
;         if (kt + 2 < nk) {
; #pragma unroll
;           for (int j = 0; j < APT; ++j) ra[j] = *(const u32x4*)(Ap + (size_t)j * RSTEP * g.lda + (kt + 2) * BK);
; #pragma unroll
;           for (int j = 0; j < BPT; ++j) rb[j] = *(const u32x4*)(Bp + (size_t)j * RSTEP * g.ldb + (kt + 2) * BK);
;         }
;       }
;       bf16x8 af[NKK][MF], bfr[NKK][2];
; #pragma unroll
;       for (int kk = 0; kk < NKK; ++kk) {
; #pragma unroll
;         for (int ni = 0; ni < 2; ++ni) bfr[kk][ni] = *(const bf16x8*)(sB + (wn * 64 + ni * 32 + l31) * LS + kk * 16 + h * 8);
; #pragma unroll
;         for (int mi = 0; mi < MF; ++mi) af[kk][mi] = *(const bf16x8*)(sA + (wm * (MF * 32) + mi * 32 + l31) * LS + kk * 16 + h * 8);
;       }
;       __builtin_amdgcn_sched_barrier(0);
; #pragma unroll
;       for (int kk = 0; kk < NKK; ++kk)
; #pragma unroll
;         for (int mi = 0; mi < MF; ++mi)
; #pragma unroll
;           for (int ni = 0; ni < 2; ++ni) acc[mi][ni] = MFMA32(bfr[kk][ni], af[kk][mi], acc[mi][ni]);
;     }
.LBB0_41:
	v_lshl_add_u64 v[78:79], v[70:71], 0, s[4:5]
	s_mov_b32 s9, 0xe7ac000
	v_add_co_u32_e32 v126, vcc, s9, v78
	s_mov_b32 s9, 0xe7d8000
	s_nop 0
	v_addc_co_u32_e32 v127, vcc, 0, v79, vcc
	v_add_co_u32_e32 v128, vcc, s9, v78
	v_lshl_add_u64 v[94:95], v[68:69], 0, s[4:5]
	s_nop 0
	v_addc_co_u32_e32 v129, vcc, 0, v79, vcc
	v_add_co_u32_e32 v130, vcc, s10, v94
	s_waitcnt lgkmcnt(0)
	s_nop 0
	v_addc_co_u32_e32 v131, vcc, 0, v95, vcc
	v_add_co_u32_e32 v132, vcc, s11, v94
	s_barrier
	s_nop 0
	v_addc_co_u32_e32 v133, vcc, 0, v95, vcc
	v_add_co_u32_e32 v134, vcc, s12, v94
	s_nop 1
	v_addc_co_u32_e32 v135, vcc, 0, v95, vcc
	v_add_co_u32_e32 v136, vcc, s13, v94
	global_load_dwordx4 v[78:81], v[126:127], off offset:256
	global_load_dwordx4 v[82:85], v[128:129], off offset:256
	global_load_dwordx4 v[86:89], v[130:131], off offset:256
	global_load_dwordx4 v[90:93], v[132:133], off offset:256
	v_addc_co_u32_e32 v137, vcc, 0, v95, vcc
	global_load_dwordx4 v[94:97], v[134:135], off offset:256
	global_load_dwordx4 v[98:101], v[136:137], off offset:256
	s_waitcnt vmcnt(6)
	ds_write_b128 v75, v[56:59] offset:27648
	ds_write_b128 v75, v[52:55] offset:32256
	ds_write_b128 v75, v[48:51] offset:36864
	ds_write_b128 v75, v[44:47] offset:41472
	ds_write_b128 v75, v[40:43] offset:46080
	ds_write_b128 v75, v[36:39] offset:50688
	ds_read_b128 v[36:39], v76 offset:9216
	ds_read_b128 v[40:43], v76 offset:9248
	ds_read_b128 v[44:47], v76 offset:13824
	ds_read_b128 v[48:51], v76 offset:13856
	ds_read_b128 v[52:55], v77
	ds_read_b128 v[56:59], v77 offset:32
	ds_read_b128 v[102:105], v76 offset:9280
	ds_read_b128 v[106:109], v76 offset:9312
	ds_read_b128 v[110:113], v76 offset:13888
	ds_read_b128 v[114:117], v76 offset:13920
	ds_read_b128 v[118:121], v77 offset:64
	ds_read_b128 v[122:125], v77 offset:96
	s_waitcnt lgkmcnt(7)
	v_mfma_f32_32x32x16_bf16 v[4:19], v[36:39], v[52:55], v[4:19]
	s_waitcnt lgkmcnt(0)
	s_barrier
	v_mfma_f32_32x32x16_bf16 v[20:35], v[44:47], v[52:55], v[20:35]
	v_mfma_f32_32x32x16_bf16 v[4:19], v[40:43], v[56:59], v[4:19]
	v_mfma_f32_32x32x16_bf16 v[20:35], v[48:51], v[56:59], v[20:35]
	global_load_dwordx4 v[56:59], v[126:127], off offset:384
	global_load_dwordx4 v[52:55], v[128:129], off offset:384
	global_load_dwordx4 v[48:51], v[130:131], off offset:384
	global_load_dwordx4 v[44:47], v[132:133], off offset:384
	global_load_dwordx4 v[40:43], v[134:135], off offset:384
	global_load_dwordx4 v[36:39], v[136:137], off offset:384
	s_waitcnt vmcnt(11)
	ds_write_b128 v75, v[78:81]
	s_waitcnt vmcnt(10)
	ds_write_b128 v75, v[82:85] offset:4608
	s_waitcnt vmcnt(9)
	ds_write_b128 v75, v[86:89] offset:9216
	s_waitcnt vmcnt(8)
	ds_write_b128 v75, v[90:93] offset:13824
	s_waitcnt vmcnt(7)
	ds_write_b128 v75, v[94:97] offset:18432
	s_waitcnt vmcnt(6)
	ds_write_b128 v75, v[98:101] offset:23040
	ds_read_b128 v[78:81], v76 offset:36864
	ds_read_b128 v[82:85], v76 offset:36896
	ds_read_b128 v[86:89], v76 offset:41472
	ds_read_b128 v[90:93], v76 offset:41504
	v_mfma_f32_32x32x16_bf16 v[4:19], v[102:105], v[118:121], v[4:19]
	v_mfma_f32_32x32x16_bf16 v[20:35], v[110:113], v[118:121], v[20:35]
	v_mfma_f32_32x32x16_bf16 v[4:19], v[106:109], v[122:125], v[4:19]
	ds_read_b128 v[94:97], v77 offset:27648
	ds_read_b128 v[98:101], v77 offset:27680
	ds_read_b128 v[102:105], v76 offset:36928
	ds_read_b128 v[106:109], v76 offset:36960
	ds_read_b128 v[110:113], v76 offset:41536
	ds_read_b128 v[118:121], v76 offset:41568
	ds_read_b128 v[126:129], v77 offset:27712
	ds_read_b128 v[130:133], v77 offset:27744
	v_mfma_f32_32x32x16_bf16 v[20:35], v[114:117], v[122:125], v[20:35]
	s_waitcnt lgkmcnt(7)
	v_mfma_f32_32x32x16_bf16 v[4:19], v[78:81], v[94:97], v[4:19]
	s_add_u32 s4, s4, 0x100
	s_addc_u32 s5, s5, 0
	s_cmpk_eq_i32 s4, 0x1500
	v_mfma_f32_32x32x16_bf16 v[20:35], v[86:89], v[94:97], v[20:35]
	s_waitcnt lgkmcnt(6)
	v_mfma_f32_32x32x16_bf16 v[4:19], v[82:85], v[98:101], v[4:19]
	v_mfma_f32_32x32x16_bf16 v[20:35], v[90:93], v[98:101], v[20:35]
	s_waitcnt lgkmcnt(1)
	v_mfma_f32_32x32x16_bf16 v[4:19], v[102:105], v[126:129], v[4:19]
	v_mfma_f32_32x32x16_bf16 v[20:35], v[110:113], v[126:129], v[20:35]
	s_waitcnt lgkmcnt(0)
	v_mfma_f32_32x32x16_bf16 v[4:19], v[106:109], v[130:133], v[4:19]
	v_mfma_f32_32x32x16_bf16 v[20:35], v[118:121], v[130:133], v[20:35]
	s_cbranch_scc0 .LBB0_41
	s_barrier
	s_waitcnt vmcnt(5)
	ds_write_b128 v75, v[56:59] offset:27648
	s_waitcnt vmcnt(4)
	ds_write_b128 v75, v[52:55] offset:32256
	s_waitcnt vmcnt(3)
	ds_write_b128 v75, v[48:51] offset:36864
	s_waitcnt vmcnt(2)
	ds_write_b128 v75, v[44:47] offset:41472
	s_waitcnt vmcnt(1)
	ds_write_b128 v75, v[40:43] offset:46080
	s_waitcnt vmcnt(0)
	ds_write_b128 v75, v[36:39] offset:50688
	ds_read_b128 v[36:39], v76 offset:9216
	ds_read_b128 v[40:43], v76 offset:9248
	ds_read_b128 v[44:47], v76 offset:13824
	ds_read_b128 v[48:51], v76 offset:13856
	ds_read_b128 v[52:55], v77
	ds_read_b128 v[56:59], v77 offset:32
	ds_read_b128 v[68:71], v76 offset:9280
	ds_read_b128 v[78:81], v76 offset:9312
	ds_read_b128 v[82:85], v76 offset:13888
	ds_read_b128 v[86:89], v76 offset:13920
	ds_read_b128 v[90:93], v77 offset:64
	ds_read_b128 v[94:97], v77 offset:96
	s_waitcnt lgkmcnt(7)
	v_mfma_f32_32x32x16_bf16 v[4:19], v[36:39], v[52:55], v[4:19]
	s_waitcnt lgkmcnt(0)
	s_barrier
; #define MFMA32(a, b, c) __builtin_amdgcn_mfma_f32_32x32x16_bf16((a), (b), (c), 0, 0, 0)
; template <int MF, int BK, class Epi>
; DI void gemm_phase_t(char* lds, const GemmDesc g, const Epi epi) {
;     ...
;       for (int kk = 0; kk < NKK; ++kk)
; #pragma unroll
;         for (int mi = 0; mi < MF; ++mi)
; #pragma unroll
;           for (int ni = 0; ni < 2; ++ni) acc[mi][ni] = MFMA32(bfr[kk][ni], af[kk][mi], acc[mi][ni]);
;     }
;     epi(acc, g.mbase + m0 + wm * (MF * 32), n0 + wn * 64, l31, h);
;   template <int MF> DI void operator()(f32x16 (&acc)[MF][2], int mb, int nb, int l31, int h) const {
; #pragma unroll
;     for (int mi = 0; mi < MF; ++mi) {
;       const int row = mb + mi * 32 + l31;
;       const float* gr = gate + (size_t)modrow(row) * 6144;
;       const float* rp = row < TL ? res_lat + (size_t)row * D : res_ctx + (size_t)(row - TL) * D;
;       float* op = row < TL ? out_lat + (size_t)row * D : out_ctx + (size_t)(row - TL) * D;
; #pragma unroll
;       for (int g4 = 0; g4 < 4; ++g4)
; #pragma unroll
;         for (int ni = 0; ni < 2; ++ni) {
;           const int col0 = nb + 16 * g4 + 8 * h + 4 * ni;
;           const float4 gt = *(const float4*)(gr + col0);
;           const float4 rv = *(const float4*)(rp + col0);
;           *(float4*)(op + col0) = make_float4(rv.x + gt.x * acc[mi][ni][4 * g4], rv.y + gt.y * acc[mi][ni][4 * g4 + 1], rv.z + gt.z * acc[mi][ni][4 * g4 + 2], rv.w + gt.w * acc[mi][ni][4 * g4 + 3]);
;         }
;     }
	v_mfma_f32_32x32x16_bf16 v[20:35], v[44:47], v[52:55], v[20:35]
	v_mfma_f32_32x32x16_bf16 v[4:19], v[40:43], v[56:59], v[4:19]
	v_mfma_f32_32x32x16_bf16 v[20:35], v[48:51], v[56:59], v[20:35]
	v_mfma_f32_32x32x16_bf16 v[4:19], v[68:71], v[90:93], v[4:19]
	v_mfma_f32_32x32x16_bf16 v[20:35], v[82:85], v[90:93], v[20:35]
	v_mfma_f32_32x32x16_bf16 v[4:19], v[78:81], v[94:97], v[4:19]
	v_mfma_f32_32x32x16_bf16 v[20:35], v[86:89], v[94:97], v[20:35]
	ds_read_b128 v[36:39], v76 offset:41472
	ds_read_b128 v[40:43], v76 offset:36864
	ds_read_b128 v[44:47], v76 offset:36896
	ds_read_b128 v[48:51], v76 offset:41504
	ds_read_b128 v[52:55], v77 offset:27648
	ds_read_b128 v[56:59], v77 offset:27680
	ds_read_b128 v[68:71], v76 offset:36928
	ds_read_b128 v[78:81], v76 offset:41536
	ds_read_b128 v[82:85], v77 offset:27712
	ds_read_b128 v[86:89], v76 offset:36960
	ds_read_b128 v[90:93], v76 offset:41568
	ds_read_b128 v[94:97], v77 offset:27744
	s_waitcnt lgkmcnt(7)
	v_mfma_f32_32x32x16_bf16 v[4:19], v[40:43], v[52:55], v[4:19]
	s_mov_b32 s4, 0x8000
	v_mfma_f32_32x32x16_bf16 v[20:35], v[36:39], v[52:55], v[20:35]
	v_add_u32_e32 v36, s8, v73
	v_min_i32_e32 v2, 0x8000, v36
	v_ashrrev_i32_e32 v2, 12, v2
	v_mul_hi_i32_i24_e32 v39, 0x6000, v2
	v_mul_i32_i24_e32 v38, 0x6000, v2
	v_add_u32_e32 v2, 0xffff8000, v36
	v_ashrrev_i32_e32 v37, 31, v36
	s_waitcnt lgkmcnt(6)
	v_mfma_f32_32x32x16_bf16 v[4:19], v[44:47], v[56:59], v[4:19]
	v_lshlrev_b64 v[40:41], 12, v[2:3]
	v_lshlrev_b64 v[42:43], 12, v[36:37]
	v_or_b32_e32 v44, s7, v74
	v_lshl_add_u64 v[42:43], s[16:17], 0, v[42:43]
	v_lshl_add_u64 v[40:41], s[18:19], 0, v[40:41]
	v_cmp_gt_i32_e32 vcc, s4, v36
	v_ashrrev_i32_e32 v45, 31, v44
	v_lshl_add_u64 v[38:39], s[2:3], 0, v[38:39]
	v_cndmask_b32_e32 v37, v41, v43, vcc
	v_cndmask_b32_e32 v36, v40, v42, vcc
	v_lshlrev_b64 v[40:41], 2, v[44:45]
	v_mfma_f32_32x32x16_bf16 v[20:35], v[48:51], v[56:59], v[20:35]
	v_lshl_add_u64 v[48:49], v[38:39], 0, v[40:41]
	v_lshl_add_u64 v[50:51], v[36:37], 0, v[40:41]
	v_readlane_b32 s4, v252, 40
	s_add_i32 s6, s6, s4
	s_cmpk_gt_i32 s6, 0xff
	s_waitcnt lgkmcnt(3)
	v_mfma_f32_32x32x16_bf16 v[4:19], v[68:71], v[82:85], v[4:19]
	v_readlane_b32 s5, v252, 41
	s_waitcnt lgkmcnt(0)
	v_mfma_f32_32x32x16_bf16 v[4:19], v[86:89], v[94:97], v[4:19]
	v_mfma_f32_32x32x16_bf16 v[20:35], v[78:81], v[82:85], v[20:35]
	v_mfma_f32_32x32x16_bf16 v[20:35], v[90:93], v[94:97], v[20:35]
	global_load_dwordx4 v[118:121], v[48:49], off
	global_load_dwordx4 v[150:153], v[50:51], off
	global_load_dwordx4 v[122:125], v[48:49], off offset:16
	global_load_dwordx4 v[154:157], v[50:51], off offset:16
	global_load_dwordx4 v[126:129], v[48:49], off offset:64
	global_load_dwordx4 v[158:161], v[50:51], off offset:64
	global_load_dwordx4 v[130:133], v[48:49], off offset:80
	global_load_dwordx4 v[162:165], v[50:51], off offset:80
	global_load_dwordx4 v[134:137], v[48:49], off offset:128
	global_load_dwordx4 v[168:171], v[50:51], off offset:128
	global_load_dwordx4 v[138:141], v[48:49], off offset:144
	global_load_dwordx4 v[172:175], v[50:51], off offset:144
	global_load_dwordx4 v[142:145], v[48:49], off offset:192
	global_load_dwordx4 v[176:179], v[50:51], off offset:192
	global_load_dwordx4 v[146:149], v[48:49], off offset:208
	global_load_dwordx4 v[180:183], v[50:51], off offset:208
	s_waitcnt vmcnt(0)
	s_nop 4
	v_fma_f32 v4, v4, v118, v150
	v_fma_f32 v5, v5, v119, v151
	v_fma_f32 v6, v6, v120, v152
	v_fma_f32 v7, v7, v121, v153
	global_store_dwordx4 v[50:51], v[4:7], off
	v_fma_f32 v20, v20, v122, v154
	v_fma_f32 v21, v21, v123, v155
	v_fma_f32 v22, v22, v124, v156
	v_fma_f32 v23, v23, v125, v157
	global_store_dwordx4 v[50:51], v[20:23], off offset:16
	v_fma_f32 v8, v8, v126, v158
	v_fma_f32 v9, v9, v127, v159
	v_fma_f32 v10, v10, v128, v160
	v_fma_f32 v11, v11, v129, v161
	global_store_dwordx4 v[50:51], v[8:11], off offset:64
	v_fma_f32 v24, v24, v130, v162
	v_fma_f32 v25, v25, v131, v163
	v_fma_f32 v26, v26, v132, v164
	v_fma_f32 v27, v27, v133, v165
	global_store_dwordx4 v[50:51], v[24:27], off offset:80
	v_fma_f32 v12, v12, v134, v168
	v_fma_f32 v13, v13, v135, v169
	v_fma_f32 v14, v14, v136, v170
	v_fma_f32 v15, v15, v137, v171
	global_store_dwordx4 v[50:51], v[12:15], off offset:128
	v_fma_f32 v28, v28, v138, v172
	v_fma_f32 v29, v29, v139, v173
	v_fma_f32 v30, v30, v140, v174
	v_fma_f32 v31, v31, v141, v175
	global_store_dwordx4 v[50:51], v[28:31], off offset:144
	v_fma_f32 v16, v16, v142, v176
	v_fma_f32 v17, v17, v143, v177
	v_fma_f32 v18, v18, v144, v178
	v_fma_f32 v19, v19, v145, v179
	global_store_dwordx4 v[50:51], v[16:19], off offset:192
	v_fma_f32 v32, v32, v146, v180
	v_fma_f32 v33, v33, v147, v181
	v_fma_f32 v34, v34, v148, v182
	v_fma_f32 v35, v35, v149, v183
	global_store_dwordx4 v[50:51], v[32:35], off offset:208
	s_cbranch_scc0 .LBB0_40

; #define MFMA32(a, b, c) __builtin_amdgcn_mfma_f32_32x32x16_bf16((a), (b), (c), 0, 0, 0)
; template <int MF, int BK, class Epi>
; DI void gemm_phase_t(char* lds, const GemmDesc g, const Epi epi) {
;     ...
;     for (int kt = 0; kt < nk; ++kt) {
;       __syncthreads();
;       const u16* sA = sbase + (kt & 1) * STG;
;       const u16* sB = sA + BM * LS;
;       if (kt + 1 < nk) {
;         u16* nA = sbase + ((kt + 1) & 1) * STG;
; #pragma unroll
;         for (int j = 0; j < APT; ++j) *(u32x4*)(nA + (lr + RSTEP * j) * LS + lc * 8) = ra[j];
; #pragma unroll
;         for (int j = 0; j < BPT; ++j) *(u32x4*)(nA + BM * LS + (lr + RSTEP * j) * LS + lc * 8) = rb[j];
;         if (kt + 2 < nk) {
; #pragma unroll
;           for (int j = 0; j < APT; ++j) ra[j] = *(const u32x4*)(Ap + (size_t)j * RSTEP * g.lda + (kt + 2) * BK);
; #pragma unroll
;           for (int j = 0; j < BPT; ++j) rb[j] = *(const u32x4*)(Bp + (size_t)j * RSTEP * g.ldb + (kt + 2) * BK);
;         }
;       }
;       bf16x8 af[NKK][MF], bfr[NKK][2];
; #pragma unroll
;       for (int kk = 0; kk < NKK; ++kk) {
; #pragma unroll
;         for (int ni = 0; ni < 2; ++ni) bfr[kk][ni] = *(const bf16x8*)(sB + (wn * 64 + ni * 32 + l31) * LS + kk * 16 + h * 8);
; #pragma unroll
;         for (int mi = 0; mi < MF; ++mi) af[kk][mi] = *(const bf16x8*)(sA + (wm * (MF * 32) + mi * 32 + l31) * LS + kk * 16 + h * 8);
;       }
;       __builtin_amdgcn_sched_barrier(0);
; #pragma unroll
;       for (int kk = 0; kk < NKK; ++kk)
; #pragma unroll
;         for (int mi = 0; mi < MF; ++mi)
; #pragma unroll
;           for (int ni = 0; ni < 2; ++ni) acc[mi][ni] = MFMA32(bfr[kk][ni], af[kk][mi], acc[mi][ni]);
;     }
.Ldma_op_loop:
	s_waitcnt vmcnt(0)
	s_waitcnt lgkmcnt(0)
	s_barrier
	s_add_i32 m0, s100, 0x0
	s_nop 0
	global_load_lds_dwordx4 v108, s[12:13]
	s_add_i32 m0, s100, 0x1000
	s_nop 0
	global_load_lds_dwordx4 v109, s[12:13]
	s_add_i32 m0, s100, 0x2000
	s_nop 0
	global_load_lds_dwordx4 v110, s[12:13]
	s_add_i32 m0, s100, 0x3000
	s_nop 0
	global_load_lds_dwordx4 v111, s[12:13]
	s_add_i32 m0, s100, 0x4000
	s_nop 0
	global_load_lds_dwordx4 v108, s[14:15]
	s_add_i32 m0, s100, 0x5000
	s_nop 0
	global_load_lds_dwordx4 v109, s[14:15]
	s_add_i32 m0, s100, 0x6000
	s_nop 0
	global_load_lds_dwordx4 v110, s[14:15]
	s_add_i32 m0, s100, 0x7000
	s_nop 0
	global_load_lds_dwordx4 v111, s[14:15]
	s_add_u32 s12, s12, 0x80
	s_addc_u32 s13, s13, 0
	s_add_u32 s14, s14, 0x80
	s_addc_u32 s15, s15, 0
	ds_read_b128 v[150:153], v234 offset:32768
	ds_read_b128 v[154:157], v234 offset:36864
	ds_read_b128 v[158:161], v238 offset:32768
	ds_read_b128 v[162:165], v238 offset:36864
	ds_read_b128 v[168:171], v235 offset:32768
	ds_read_b128 v[172:175], v235 offset:36864
	ds_read_b128 v[176:179], v239 offset:32768
	ds_read_b128 v[180:183], v239 offset:36864
	ds_read_b128 v[184:187], v236 offset:32768
	ds_read_b128 v[188:191], v236 offset:36864
	ds_read_b128 v[192:195], v240 offset:32768
	ds_read_b128 v[198:201], v240 offset:36864
	ds_read_b128 v[218:221], v237 offset:32768
	ds_read_b128 v[222:225], v237 offset:36864
	ds_read_b128 v[226:229], v241 offset:32768
	ds_read_b128 v[230:233], v241 offset:36864
	v_mfma_f32_32x32x16_bf16 v[52:67], v[68:71], v[76:79], v[52:67]
	v_mfma_f32_32x32x16_bf16 v[36:51], v[72:75], v[76:79], v[36:51]
	v_mfma_f32_32x32x16_bf16 v[20:35], v[68:71], v[80:83], v[20:35]
	v_mfma_f32_32x32x16_bf16 v[4:19], v[72:75], v[80:83], v[4:19]
	v_mfma_f32_32x32x16_bf16 v[52:67], v[84:87], v[92:95], v[52:67]
	v_mfma_f32_32x32x16_bf16 v[36:51], v[88:91], v[92:95], v[36:51]
	v_mfma_f32_32x32x16_bf16 v[20:35], v[84:87], v[96:99], v[20:35]
	v_mfma_f32_32x32x16_bf16 v[4:19], v[88:91], v[96:99], v[4:19]
	v_mfma_f32_32x32x16_bf16 v[52:67], v[118:121], v[126:129], v[52:67]
	v_mfma_f32_32x32x16_bf16 v[36:51], v[122:125], v[126:129], v[36:51]
	v_mfma_f32_32x32x16_bf16 v[20:35], v[118:121], v[130:133], v[20:35]
	v_mfma_f32_32x32x16_bf16 v[4:19], v[122:125], v[130:133], v[4:19]
	v_mfma_f32_32x32x16_bf16 v[52:67], v[134:137], v[142:145], v[52:67]
	v_mfma_f32_32x32x16_bf16 v[36:51], v[138:141], v[142:145], v[36:51]
	v_mfma_f32_32x32x16_bf16 v[20:35], v[134:137], v[146:149], v[20:35]
	v_mfma_f32_32x32x16_bf16 v[4:19], v[138:141], v[146:149], v[4:19]
	s_waitcnt vmcnt(0)
	s_waitcnt lgkmcnt(0)
	s_barrier
	s_add_i32 m0, s100, 0x8000
	s_nop 0
	global_load_lds_dwordx4 v108, s[12:13]
	s_add_i32 m0, s100, 0x9000
	s_nop 0
	global_load_lds_dwordx4 v109, s[12:13]
	s_add_i32 m0, s100, 0xa000
	s_nop 0
	global_load_lds_dwordx4 v110, s[12:13]
	s_add_i32 m0, s100, 0xb000
	s_nop 0
	global_load_lds_dwordx4 v111, s[12:13]
	s_add_i32 m0, s100, 0xc000
	s_nop 0
	global_load_lds_dwordx4 v108, s[14:15]
	s_add_i32 m0, s100, 0xd000
	s_nop 0
	global_load_lds_dwordx4 v109, s[14:15]
	s_add_i32 m0, s100, 0xe000
	s_nop 0
	global_load_lds_dwordx4 v110, s[14:15]
	s_add_i32 m0, s100, 0xf000
	s_nop 0
	global_load_lds_dwordx4 v111, s[14:15]
	s_add_u32 s12, s12, 0x80
	s_addc_u32 s13, s13, 0
	s_add_u32 s14, s14, 0x80
	s_addc_u32 s15, s15, 0
	ds_read_b128 v[68:71], v234
	ds_read_b128 v[72:75], v234 offset:4096
	ds_read_b128 v[76:79], v238
	ds_read_b128 v[80:83], v238 offset:4096
	ds_read_b128 v[84:87], v235
	ds_read_b128 v[88:91], v235 offset:4096
	ds_read_b128 v[92:95], v239
	ds_read_b128 v[96:99], v239 offset:4096
	ds_read_b128 v[118:121], v236
	ds_read_b128 v[122:125], v236 offset:4096
	ds_read_b128 v[126:129], v240
	ds_read_b128 v[130:133], v240 offset:4096
	ds_read_b128 v[134:137], v237
	ds_read_b128 v[138:141], v237 offset:4096
	ds_read_b128 v[142:145], v241
	ds_read_b128 v[146:149], v241 offset:4096
	v_mfma_f32_32x32x16_bf16 v[52:67], v[150:153], v[158:161], v[52:67]
	v_mfma_f32_32x32x16_bf16 v[36:51], v[154:157], v[158:161], v[36:51]
	v_mfma_f32_32x32x16_bf16 v[20:35], v[150:153], v[162:165], v[20:35]
	v_mfma_f32_32x32x16_bf16 v[4:19], v[154:157], v[162:165], v[4:19]
	v_mfma_f32_32x32x16_bf16 v[52:67], v[168:171], v[176:179], v[52:67]
	v_mfma_f32_32x32x16_bf16 v[36:51], v[172:175], v[176:179], v[36:51]
	v_mfma_f32_32x32x16_bf16 v[20:35], v[168:171], v[180:183], v[20:35]
	v_mfma_f32_32x32x16_bf16 v[4:19], v[172:175], v[180:183], v[4:19]
	v_mfma_f32_32x32x16_bf16 v[52:67], v[184:187], v[192:195], v[52:67]
	v_mfma_f32_32x32x16_bf16 v[36:51], v[188:191], v[192:195], v[36:51]
	v_mfma_f32_32x32x16_bf16 v[20:35], v[184:187], v[198:201], v[20:35]
	v_mfma_f32_32x32x16_bf16 v[4:19], v[188:191], v[198:201], v[4:19]
	v_mfma_f32_32x32x16_bf16 v[52:67], v[218:221], v[226:229], v[52:67]
	v_mfma_f32_32x32x16_bf16 v[36:51], v[222:225], v[226:229], v[36:51]
	v_mfma_f32_32x32x16_bf16 v[20:35], v[218:221], v[230:233], v[20:35]
	v_mfma_f32_32x32x16_bf16 v[4:19], v[222:225], v[230:233], v[4:19]
	s_add_i32 s9, s9, -1
	s_cmp_lg_u32 s9, 0
	s_cbranch_scc1 .Ldma_op_loop
	s_waitcnt vmcnt(0)
	s_waitcnt lgkmcnt(0)
	s_barrier
; #define MFMA32(a, b, c) __builtin_amdgcn_mfma_f32_32x32x16_bf16((a), (b), (c), 0, 0, 0)
; template <int MF, int BK, class Epi>
; DI void gemm_phase_t(char* lds, const GemmDesc g, const Epi epi) {
;     ...
;       for (int kk = 0; kk < NKK; ++kk) {
; #pragma unroll
;         for (int ni = 0; ni < 2; ++ni) bfr[kk][ni] = *(const bf16x8*)(sB + (wn * 64 + ni * 32 + l31) * LS + kk * 16 + h * 8);
; #pragma unroll
;         for (int mi = 0; mi < MF; ++mi) af[kk][mi] = *(const bf16x8*)(sA + (wm * (MF * 32) + mi * 32 + l31) * LS + kk * 16 + h * 8);
;       }
;       __builtin_amdgcn_sched_barrier(0);
; #pragma unroll
;       for (int kk = 0; kk < NKK; ++kk)
; #pragma unroll
;         for (int mi = 0; mi < MF; ++mi)
; #pragma unroll
;           for (int ni = 0; ni < 2; ++ni) acc[mi][ni] = MFMA32(bfr[kk][ni], af[kk][mi], acc[mi][ni]);
;   template <int MF> DI void operator()(f32x16 (&acc)[MF][2], int mb, int nb, int l31, int h) const {
; #pragma unroll
;     for (int mi = 0; mi < MF; ++mi) {
;       const int row = mb + mi * 32 + l31;
;       const float* gr = gate + (size_t)modrow(row) * 6144;
;       const float* rp = row < TL ? res_lat + (size_t)row * D : res_ctx + (size_t)(row - TL) * D;
;       float* op = row < TL ? out_lat + (size_t)row * D : out_ctx + (size_t)(row - TL) * D;
; #pragma unroll
;       for (int g4 = 0; g4 < 4; ++g4)
; #pragma unroll
;         for (int ni = 0; ni < 2; ++ni) {
;           const int col0 = nb + 16 * g4 + 8 * h + 4 * ni;
;           const float4 gt = *(const float4*)(gr + col0);
;           const float4 rv = *(const float4*)(rp + col0);
;           *(float4*)(op + col0) = make_float4(rv.x + gt.x * acc[mi][ni][4 * g4], rv.y + gt.y * acc[mi][ni][4 * g4 + 1], rv.z + gt.z * acc[mi][ni][4 * g4 + 2], rv.w + gt.w * acc[mi][ni][4 * g4 + 3]);
	ds_read_b128 v[150:153], v234 offset:32768
	ds_read_b128 v[154:157], v234 offset:36864
	ds_read_b128 v[158:161], v238 offset:32768
	ds_read_b128 v[162:165], v238 offset:36864
	ds_read_b128 v[168:171], v235 offset:32768
	ds_read_b128 v[172:175], v235 offset:36864
	ds_read_b128 v[176:179], v239 offset:32768
	ds_read_b128 v[180:183], v239 offset:36864
	ds_read_b128 v[184:187], v236 offset:32768
	ds_read_b128 v[188:191], v236 offset:36864
	ds_read_b128 v[192:195], v240 offset:32768
	ds_read_b128 v[198:201], v240 offset:36864
	ds_read_b128 v[218:221], v237 offset:32768
	ds_read_b128 v[222:225], v237 offset:36864
	ds_read_b128 v[226:229], v241 offset:32768
	ds_read_b128 v[230:233], v241 offset:36864
	v_mfma_f32_32x32x16_bf16 v[52:67], v[68:71], v[76:79], v[52:67]
	v_mfma_f32_32x32x16_bf16 v[36:51], v[72:75], v[76:79], v[36:51]
	v_mfma_f32_32x32x16_bf16 v[20:35], v[68:71], v[80:83], v[20:35]
	v_mfma_f32_32x32x16_bf16 v[4:19], v[72:75], v[80:83], v[4:19]
	v_mfma_f32_32x32x16_bf16 v[52:67], v[84:87], v[92:95], v[52:67]
	v_mfma_f32_32x32x16_bf16 v[36:51], v[88:91], v[92:95], v[36:51]
	v_mfma_f32_32x32x16_bf16 v[20:35], v[84:87], v[96:99], v[20:35]
	v_mfma_f32_32x32x16_bf16 v[4:19], v[88:91], v[96:99], v[4:19]
	v_mfma_f32_32x32x16_bf16 v[52:67], v[118:121], v[126:129], v[52:67]
	v_mfma_f32_32x32x16_bf16 v[36:51], v[122:125], v[126:129], v[36:51]
	v_mfma_f32_32x32x16_bf16 v[20:35], v[118:121], v[130:133], v[20:35]
	v_mfma_f32_32x32x16_bf16 v[4:19], v[122:125], v[130:133], v[4:19]
	v_mfma_f32_32x32x16_bf16 v[52:67], v[134:137], v[142:145], v[52:67]
	v_mfma_f32_32x32x16_bf16 v[36:51], v[138:141], v[142:145], v[36:51]
	v_mfma_f32_32x32x16_bf16 v[20:35], v[134:137], v[146:149], v[20:35]
	v_mfma_f32_32x32x16_bf16 v[4:19], v[138:141], v[146:149], v[4:19]
	s_waitcnt lgkmcnt(0)
	v_mfma_f32_32x32x16_bf16 v[52:67], v[150:153], v[158:161], v[52:67]
	v_mfma_f32_32x32x16_bf16 v[36:51], v[154:157], v[158:161], v[36:51]
	v_mfma_f32_32x32x16_bf16 v[20:35], v[150:153], v[162:165], v[20:35]
	v_mfma_f32_32x32x16_bf16 v[4:19], v[154:157], v[162:165], v[4:19]
	v_mfma_f32_32x32x16_bf16 v[52:67], v[168:171], v[176:179], v[52:67]
	v_mfma_f32_32x32x16_bf16 v[36:51], v[172:175], v[176:179], v[36:51]
	v_mfma_f32_32x32x16_bf16 v[20:35], v[168:171], v[180:183], v[20:35]
	v_mfma_f32_32x32x16_bf16 v[4:19], v[172:175], v[180:183], v[4:19]
	v_mfma_f32_32x32x16_bf16 v[52:67], v[184:187], v[192:195], v[52:67]
	v_mfma_f32_32x32x16_bf16 v[36:51], v[188:191], v[192:195], v[36:51]
	v_mfma_f32_32x32x16_bf16 v[20:35], v[184:187], v[198:201], v[20:35]
	v_mfma_f32_32x32x16_bf16 v[4:19], v[188:191], v[198:201], v[4:19]
	v_mfma_f32_32x32x16_bf16 v[52:67], v[218:221], v[226:229], v[52:67]
	v_mfma_f32_32x32x16_bf16 v[36:51], v[222:225], v[226:229], v[36:51]
	v_mfma_f32_32x32x16_bf16 v[20:35], v[218:221], v[230:233], v[20:35]
	v_mfma_f32_32x32x16_bf16 v[4:19], v[222:225], v[230:233], v[4:19]
	v_readlane_b32 s10, v253, 26
	v_readlane_b32 s11, v253, 27
	v_or_b32_e32 v68, s7, v114
	v_mov_b32_e32 v88, s10
	v_mov_b32_e32 v89, s31
	v_mov_b32_e32 v90, s29
	v_mov_b32_e32 v91, s30
	v_add_u32_e32 v84, s6, v113
	v_min_i32_e32 v69, 0x8000, v84
	s_mov_b32 s6, 0x8000
	v_ashrrev_i32_e32 v69, 12, v69
	v_cmp_gt_i32_e32 vcc, s6, v84
	v_readlane_b32 s6, v253, 28
	v_mul_hi_i32_i24_e32 v71, 0x6000, v69
	v_mul_i32_i24_e32 v70, 0x6000, v69
	v_add_u32_e32 v69, 0xffff8000, v84
	v_ashrrev_i32_e32 v72, 31, v84
	v_readlane_b32 s7, v253, 29
	v_cndmask_b32_e32 v73, 0, v72, vcc
	v_cndmask_b32_e32 v72, v69, v84, vcc
	v_mov_b32_e32 v85, s7
	v_mov_b32_e32 v86, s11
	v_mov_b32_e32 v87, s6
	v_mov_b32_e32 v92, s28
	v_ashrrev_i32_e32 v69, 31, v68
	v_lshl_add_u64 v[70:71], s[0:1], 0, v[70:71]
	v_cndmask_b32_e32 v75, v85, v86, vcc
	v_cndmask_b32_e32 v74, v87, v88, vcc
	v_lshlrev_b64 v[72:73], 12, v[72:73]
	v_cndmask_b32_e32 v77, v89, v90, vcc
	v_cndmask_b32_e32 v76, v91, v92, vcc
	v_lshlrev_b64 v[68:69], 2, v[68:69]
	v_lshl_add_u64 v[74:75], v[74:75], 0, v[72:73]
	v_lshl_add_u64 v[72:73], v[76:77], 0, v[72:73]
	v_lshl_add_u64 v[78:79], v[70:71], 0, v[68:69]
	v_lshl_add_u64 v[80:81], v[74:75], 0, v[68:69]
	v_lshl_add_u64 v[82:83], v[72:73], 0, v[68:69]
	s_movk_i32 s6, 0x7fe0
	v_cmp_gt_i32_e32 vcc, s6, v84
	v_readlane_b32 s6, v252, 40
	s_add_i32 s8, s8, s6
	s_cmpk_gt_i32 s8, 0x7ff
	v_readlane_b32 s7, v252, 41
	v_or_b32_e32 v76, 32, v84
	v_cndmask_b32_e32 v75, v89, v90, vcc
	v_cndmask_b32_e32 v74, v91, v92, vcc
	v_ashrrev_i32_e32 v70, 31, v76
	v_add_u32_e32 v72, 0xffff8020, v84
	v_cndmask_b32_e32 v71, 0, v70, vcc
	v_cndmask_b32_e32 v70, v72, v76, vcc
	v_cndmask_b32_e32 v73, v85, v86, vcc
	v_cndmask_b32_e32 v72, v87, v88, vcc
	v_lshlrev_b64 v[70:71], 12, v[70:71]
	v_lshl_add_u64 v[72:73], v[72:73], 0, v[70:71]
	v_lshl_add_u64 v[70:71], v[74:75], 0, v[70:71]
	v_lshl_add_u64 v[96:97], v[72:73], 0, v[68:69]
	v_lshl_add_u64 v[98:99], v[70:71], 0, v[68:69]
	global_load_dwordx4 v[118:121], v[78:79], off
	global_load_dwordx4 v[150:153], v[80:81], off
	global_load_dwordx4 v[122:125], v[78:79], off offset:16
	global_load_dwordx4 v[154:157], v[80:81], off offset:16
	global_load_dwordx4 v[126:129], v[78:79], off offset:64
	global_load_dwordx4 v[158:161], v[80:81], off offset:64
	global_load_dwordx4 v[130:133], v[78:79], off offset:80
	global_load_dwordx4 v[162:165], v[80:81], off offset:80
	global_load_dwordx4 v[134:137], v[78:79], off offset:128
	global_load_dwordx4 v[168:171], v[80:81], off offset:128
	global_load_dwordx4 v[138:141], v[78:79], off offset:144
	global_load_dwordx4 v[172:175], v[80:81], off offset:144
	global_load_dwordx4 v[142:145], v[78:79], off offset:192
	global_load_dwordx4 v[176:179], v[80:81], off offset:192
	global_load_dwordx4 v[146:149], v[78:79], off offset:208
	global_load_dwordx4 v[180:183], v[80:81], off offset:208
	global_load_dwordx4 v[184:187], v[96:97], off
	global_load_dwordx4 v[188:191], v[96:97], off offset:16
	global_load_dwordx4 v[192:195], v[96:97], off offset:64
	global_load_dwordx4 v[198:201], v[96:97], off offset:80
	global_load_dwordx4 v[218:221], v[96:97], off offset:128
	global_load_dwordx4 v[222:225], v[96:97], off offset:144
	global_load_dwordx4 v[226:229], v[96:97], off offset:192
	global_load_dwordx4 v[230:233], v[96:97], off offset:208
	s_waitcnt vmcnt(8)
;   template <int MF> DI void operator()(f32x16 (&acc)[MF][2], int mb, int nb, int l31, int h) const {
; #pragma unroll
;     for (int mi = 0; mi < MF; ++mi) {
;       const int row = mb + mi * 32 + l31;
;       const float* gr = gate + (size_t)modrow(row) * 6144;
;       const float* rp = row < TL ? res_lat + (size_t)row * D : res_ctx + (size_t)(row - TL) * D;
;       float* op = row < TL ? out_lat + (size_t)row * D : out_ctx + (size_t)(row - TL) * D;
; #pragma unroll
;       for (int g4 = 0; g4 < 4; ++g4)
; #pragma unroll
;         for (int ni = 0; ni < 2; ++ni) {
;           const int col0 = nb + 16 * g4 + 8 * h + 4 * ni;
;           const float4 gt = *(const float4*)(gr + col0);
;           const float4 rv = *(const float4*)(rp + col0);
;           *(float4*)(op + col0) = make_float4(rv.x + gt.x * acc[mi][ni][4 * g4], rv.y + gt.y * acc[mi][ni][4 * g4 + 1], rv.z + gt.z * acc[mi][ni][4 * g4 + 2], rv.w + gt.w * acc[mi][ni][4 * g4 + 3]);
;         }
;     }
	s_nop 4
	v_fma_f32 v52, v52, v118, v150
	v_fma_f32 v53, v53, v119, v151
	v_fma_f32 v54, v54, v120, v152
	v_fma_f32 v55, v55, v121, v153
	global_store_dwordx4 v[82:83], v[52:55], off
	v_fma_f32 v36, v36, v122, v154
	v_fma_f32 v37, v37, v123, v155
	v_fma_f32 v38, v38, v124, v156
	v_fma_f32 v39, v39, v125, v157
	global_store_dwordx4 v[82:83], v[36:39], off offset:16
	v_fma_f32 v56, v56, v126, v158
	v_fma_f32 v57, v57, v127, v159
	v_fma_f32 v58, v58, v128, v160
	v_fma_f32 v59, v59, v129, v161
	global_store_dwordx4 v[82:83], v[56:59], off offset:64
	v_fma_f32 v40, v40, v130, v162
	v_fma_f32 v41, v41, v131, v163
	v_fma_f32 v42, v42, v132, v164
	v_fma_f32 v43, v43, v133, v165
	global_store_dwordx4 v[82:83], v[40:43], off offset:80
	v_fma_f32 v60, v60, v134, v168
	v_fma_f32 v61, v61, v135, v169
	v_fma_f32 v62, v62, v136, v170
	v_fma_f32 v63, v63, v137, v171
	global_store_dwordx4 v[82:83], v[60:63], off offset:128
	v_fma_f32 v44, v44, v138, v172
	v_fma_f32 v45, v45, v139, v173
	v_fma_f32 v46, v46, v140, v174
	v_fma_f32 v47, v47, v141, v175
	global_store_dwordx4 v[82:83], v[44:47], off offset:144
	v_fma_f32 v64, v64, v142, v176
	v_fma_f32 v65, v65, v143, v177
	v_fma_f32 v66, v66, v144, v178
	v_fma_f32 v67, v67, v145, v179
	global_store_dwordx4 v[82:83], v[64:67], off offset:192
	v_fma_f32 v48, v48, v146, v180
	v_fma_f32 v49, v49, v147, v181
	v_fma_f32 v50, v50, v148, v182
	v_fma_f32 v51, v51, v149, v183
	global_store_dwordx4 v[82:83], v[48:51], off offset:208
	s_waitcnt vmcnt(8)
	v_fma_f32 v20, v20, v118, v184
	v_fma_f32 v21, v21, v119, v185
	v_fma_f32 v22, v22, v120, v186
	v_fma_f32 v23, v23, v121, v187
	global_store_dwordx4 v[98:99], v[20:23], off
	v_fma_f32 v4, v4, v122, v188
	v_fma_f32 v5, v5, v123, v189
	v_fma_f32 v6, v6, v124, v190
	v_fma_f32 v7, v7, v125, v191
	global_store_dwordx4 v[98:99], v[4:7], off offset:16
	v_fma_f32 v24, v24, v126, v192
	v_fma_f32 v25, v25, v127, v193
	v_fma_f32 v26, v26, v128, v194
	v_fma_f32 v27, v27, v129, v195
	global_store_dwordx4 v[98:99], v[24:27], off offset:64
	v_fma_f32 v8, v8, v130, v198
	v_fma_f32 v9, v9, v131, v199
	v_fma_f32 v10, v10, v132, v200
	v_fma_f32 v11, v11, v133, v201
	global_store_dwordx4 v[98:99], v[8:11], off offset:80
	v_fma_f32 v28, v28, v134, v218
	v_fma_f32 v29, v29, v135, v219
	v_fma_f32 v30, v30, v136, v220
	v_fma_f32 v31, v31, v137, v221
	global_store_dwordx4 v[98:99], v[28:31], off offset:128
	v_fma_f32 v12, v12, v138, v222
	v_fma_f32 v13, v13, v139, v223
	v_fma_f32 v14, v14, v140, v224
	v_fma_f32 v15, v15, v141, v225
	global_store_dwordx4 v[98:99], v[12:15], off offset:144
	v_fma_f32 v32, v32, v142, v226
	v_fma_f32 v33, v33, v143, v227
	v_fma_f32 v34, v34, v144, v228
	v_fma_f32 v35, v35, v145, v229
	global_store_dwordx4 v[98:99], v[32:35], off offset:192
	v_fma_f32 v16, v16, v146, v230
	v_fma_f32 v17, v17, v147, v231
	v_fma_f32 v18, v18, v148, v232
	v_fma_f32 v19, v19, v149, v233
	global_store_dwordx4 v[98:99], v[16:19], off offset:208
	s_cbranch_scc0 .LBB0_305

; DI int bid_l() { int t = blockIdx.x; asm volatile("" : "+s"(t)); return t; }
; DI f32x16 zero16() { f32x16 z; for (int i = 0; i < 16; ++i) z[i] = 0.f; return z; }
; template <int MF, int BK, class Epi>
; DI void gemm_phase_t(char* lds, const GemmDesc g, const Epi epi) {
;     ...
;   for (int t = bid_l(); t < ntiles; t += gridDim.x) {
;     const int tn = t % ntn, tm = t / ntn;
;     const int m0 = tm * BM, n0 = tn * 128;
;     const u16* Ap = g.A + (size_t)(m0 + lr) * g.lda + lc * 8;
;     const u16* Bp = g.Bt + (size_t)(n0 + lr) * g.ldb + lc * 8;
;     u32x4 ra[APT], rb[BPT];
; #pragma unroll
;     for (int j = 0; j < APT; ++j) ra[j] = *(const u32x4*)(Ap + (size_t)j * RSTEP * g.lda);
; #pragma unroll
;     for (int j = 0; j < BPT; ++j) rb[j] = *(const u32x4*)(Bp + (size_t)j * RSTEP * g.ldb);
; #pragma unroll
;     for (int j = 0; j < APT; ++j) *(u32x4*)(sbase + (lr + RSTEP * j) * LS + lc * 8) = ra[j];
; #pragma unroll
;     for (int j = 0; j < BPT; ++j) *(u32x4*)(sbase + BM * LS + (lr + RSTEP * j) * LS + lc * 8) = rb[j];
;     if (nk > 1) {
; #pragma unroll
;       for (int j = 0; j < APT; ++j) ra[j] = *(const u32x4*)(Ap + (size_t)j * RSTEP * g.lda + BK);
; #pragma unroll
;       for (int j = 0; j < BPT; ++j) rb[j] = *(const u32x4*)(Bp + (size_t)j * RSTEP * g.ldb + BK);
;     }
;     f32x16 acc[MF][2];
; #pragma unroll
;     for (int i = 0; i < MF; ++i)
; #pragma unroll
;       for (int j = 0; j < 2; ++j) acc[i][j] = zero16();
;     for (int kt = 0; kt < nk; ++kt) {
;       __syncthreads();
;       const u16* sA = sbase + (kt & 1) * STG;
;       const u16* sB = sA + BM * LS;
;       if (kt + 1 < nk) {
;         u16* nA = sbase + ((kt + 1) & 1) * STG;
; #pragma unroll
;         for (int j = 0; j < APT; ++j) *(u32x4*)(nA + (lr + RSTEP * j) * LS + lc * 8) = ra[j];
; #pragma unroll
;         for (int j = 0; j < BPT; ++j) *(u32x4*)(nA + BM * LS + (lr + RSTEP * j) * LS + lc * 8) = rb[j];
.LBB0_311:
	s_ashr_i32 s4, s6, 31
	s_lshr_b32 s4, s4, 29
	s_add_i32 s4, s6, s4
	s_ashr_i32 s4, s4, 3
	s_lshl_b32 s5, s4, 6
	v_add_u32_e32 v4, s5, v52
	s_lshl_b32 s4, s4, 10
	v_ashrrev_i32_e32 v5, 31, v4
	s_sub_i32 s4, s2, s4
	v_lshlrev_b64 v[4:5], 11, v[4:5]
	s_waitcnt vmcnt(1)
	v_add_u32_e32 v12, s4, v52
	v_lshl_add_u64 v[40:41], v[36:37], 0, v[4:5]
	v_ashrrev_i32_e32 v13, 31, v12
	v_add_co_u32_e32 v42, vcc, s10, v40
	v_lshlrev_b64 v[12:13], 11, v[12:13]
	s_nop 0
	v_addc_co_u32_e32 v43, vcc, 0, v41, vcc
	v_lshl_add_u64 v[44:45], v[38:39], 0, v[12:13]
	global_load_dwordx4 v[4:7], v[40:41], off
	global_load_dwordx4 v[8:11], v[42:43], off
	v_add_co_u32_e32 v46, vcc, s10, v44
	global_load_dwordx4 v[12:15], v[44:45], off
	s_nop 0
	v_addc_co_u32_e32 v47, vcc, 0, v45, vcc
	v_add_co_u32_e32 v48, vcc, s9, v44
	global_load_dwordx4 v[16:19], v[46:47], off
	s_nop 0
	v_addc_co_u32_e32 v49, vcc, 0, v45, vcc
	global_load_dwordx4 v[20:23], v[48:49], off
	v_add_co_u32_e32 v50, vcc, s11, v44
	s_nop 1
	v_addc_co_u32_e32 v51, vcc, 0, v45, vcc
	global_load_dwordx4 v[24:27], v[50:51], off
	global_load_dwordx4 v[28:31], v[40:41], off offset:128
	global_load_dwordx4 v[32:35], v[42:43], off offset:128
	global_load_dwordx4 v[58:61], v[44:45], off offset:128
	global_load_dwordx4 v[62:65], v[46:47], off offset:128
	global_load_dwordx4 v[66:69], v[48:49], off offset:128
	global_load_dwordx4 v[70:73], v[50:51], off offset:128
	s_waitcnt vmcnt(11)
	ds_write_b128 v54, v[4:7]
	s_waitcnt vmcnt(10)
	ds_write_b128 v54, v[8:11] offset:4608
	s_waitcnt vmcnt(9)
	ds_write_b128 v54, v[12:15] offset:9216
	s_waitcnt vmcnt(8)
	ds_write_b128 v54, v[16:19] offset:13824
	s_waitcnt vmcnt(7)
	ds_write_b128 v54, v[20:23] offset:18432
	s_waitcnt vmcnt(6)
	ds_write_b128 v54, v[24:27] offset:23040
	s_waitcnt lgkmcnt(0)
	s_barrier
	global_load_dwordx4 v[74:77], v[50:51], off offset:256
	global_load_dwordx4 v[78:81], v[48:49], off offset:256
	global_load_dwordx4 v[82:85], v[46:47], off offset:256
	global_load_dwordx4 v[86:89], v[44:45], off offset:256
	global_load_dwordx4 v[90:93], v[42:43], off offset:256
	global_load_dwordx4 v[94:97], v[40:41], off offset:256
	s_waitcnt vmcnt(11)
	ds_write_b128 v54, v[28:31] offset:27648
	s_waitcnt vmcnt(10)
	ds_write_b128 v54, v[32:35] offset:32256
	s_waitcnt vmcnt(9)
	ds_write_b128 v54, v[58:61] offset:36864
	s_waitcnt vmcnt(8)
	ds_write_b128 v54, v[62:65] offset:41472
	s_waitcnt vmcnt(7)
	ds_write_b128 v54, v[66:69] offset:46080
	s_waitcnt vmcnt(6)
	ds_write_b128 v54, v[70:73] offset:50688
	ds_read_b128 v[4:7], v55 offset:9216
	ds_read_b128 v[58:61], v55 offset:9248
	ds_read_b128 v[8:11], v55 offset:13824
	ds_read_b128 v[62:65], v55 offset:13856
	ds_read_b128 v[12:15], v57
	ds_read_b128 v[66:69], v57 offset:32
	ds_read_b128 v[70:73], v55 offset:9280
	ds_read_b128 v[98:101], v55 offset:9312
	ds_read_b128 v[102:105], v55 offset:13888
	ds_read_b128 v[106:109], v55 offset:13920
	ds_read_b128 v[110:113], v57 offset:64
	ds_read_b128 v[114:117], v57 offset:96
	s_waitcnt lgkmcnt(7)
	v_mfma_f32_32x32x16_bf16 v[20:35], v[4:7], v[12:15], 0
	s_waitcnt lgkmcnt(0)
	s_barrier
	s_waitcnt vmcnt(0)
	ds_write_b128 v54, v[94:97]
	ds_write_b128 v54, v[90:93] offset:4608
	ds_write_b128 v54, v[86:89] offset:9216
	ds_write_b128 v54, v[82:85] offset:13824
	ds_write_b128 v54, v[78:81] offset:18432
	ds_write_b128 v54, v[74:77] offset:23040
	v_mfma_f32_32x32x16_bf16 v[4:19], v[8:11], v[12:15], 0
	v_mfma_f32_32x32x16_bf16 v[20:35], v[58:61], v[66:69], v[20:35]
	v_mfma_f32_32x32x16_bf16 v[4:19], v[62:65], v[66:69], v[4:19]
	v_mfma_f32_32x32x16_bf16 v[20:35], v[70:73], v[110:113], v[20:35]
	global_load_dwordx4 v[58:61], v[50:51], off offset:384
	global_load_dwordx4 v[62:65], v[48:49], off offset:384
	global_load_dwordx4 v[66:69], v[46:47], off offset:384
	global_load_dwordx4 v[70:73], v[44:45], off offset:384
	global_load_dwordx4 v[74:77], v[42:43], off offset:384
	global_load_dwordx4 v[78:81], v[40:41], off offset:384
	v_mfma_f32_32x32x16_bf16 v[4:19], v[102:105], v[110:113], v[4:19]
	v_mfma_f32_32x32x16_bf16 v[20:35], v[98:101], v[114:117], v[20:35]
	v_mfma_f32_32x32x16_bf16 v[4:19], v[106:109], v[114:117], v[4:19]
	ds_read_b128 v[82:85], v55 offset:41472
	ds_read_b128 v[86:89], v55 offset:36864
	ds_read_b128 v[90:93], v55 offset:36896
	ds_read_b128 v[94:97], v55 offset:41504
	ds_read_b128 v[98:101], v57 offset:27648
	ds_read_b128 v[102:105], v57 offset:27680
	ds_read_b128 v[106:109], v55 offset:36928
	ds_read_b128 v[110:113], v55 offset:41536
	ds_read_b128 v[114:117], v57 offset:27712
	ds_read_b128 v[118:121], v55 offset:36960
	ds_read_b128 v[122:125], v55 offset:41568
	ds_read_b128 v[126:129], v57 offset:27744
	s_waitcnt lgkmcnt(0)
	s_barrier
	s_waitcnt vmcnt(0)
	ds_write_b128 v54, v[78:81] offset:27648
	ds_write_b128 v54, v[74:77] offset:32256
	ds_write_b128 v54, v[70:73] offset:36864
	ds_write_b128 v54, v[66:69] offset:41472
	ds_write_b128 v54, v[62:65] offset:46080
	ds_write_b128 v54, v[58:61] offset:50688
	global_load_dwordx4 v[58:61], v[50:51], off offset:512
	global_load_dwordx4 v[62:65], v[48:49], off offset:512
	global_load_dwordx4 v[66:69], v[46:47], off offset:512
	global_load_dwordx4 v[70:73], v[44:45], off offset:512
	global_load_dwordx4 v[74:77], v[42:43], off offset:512
	global_load_dwordx4 v[78:81], v[40:41], off offset:512
	v_mfma_f32_32x32x16_bf16 v[20:35], v[86:89], v[98:101], v[20:35]
	v_mfma_f32_32x32x16_bf16 v[4:19], v[82:85], v[98:101], v[4:19]
	v_mfma_f32_32x32x16_bf16 v[20:35], v[90:93], v[102:105], v[20:35]
	v_mfma_f32_32x32x16_bf16 v[4:19], v[94:97], v[102:105], v[4:19]
	v_mfma_f32_32x32x16_bf16 v[20:35], v[106:109], v[114:117], v[20:35]
	v_mfma_f32_32x32x16_bf16 v[4:19], v[110:113], v[114:117], v[4:19]
	v_mfma_f32_32x32x16_bf16 v[20:35], v[118:121], v[126:129], v[20:35]
	v_mfma_f32_32x32x16_bf16 v[4:19], v[122:125], v[126:129], v[4:19]
	ds_read_b128 v[82:85], v55 offset:13824
	ds_read_b128 v[86:89], v55 offset:9216
	ds_read_b128 v[90:93], v55 offset:9248
	ds_read_b128 v[94:97], v55 offset:13856
	ds_read_b128 v[98:101], v57
	ds_read_b128 v[102:105], v57 offset:32
	ds_read_b128 v[106:109], v55 offset:9280
	ds_read_b128 v[110:113], v55 offset:13888
	ds_read_b128 v[114:117], v57 offset:64
	ds_read_b128 v[118:121], v55 offset:9312
	ds_read_b128 v[122:125], v55 offset:13920
	ds_read_b128 v[126:129], v57 offset:96
	s_waitcnt lgkmcnt(0)
	s_barrier
; #define MFMA32(a, b, c) __builtin_amdgcn_mfma_f32_32x32x16_bf16((a), (b), (c), 0, 0, 0)
; template <int MF, int BK, class Epi>
; DI void gemm_phase_t(char* lds, const GemmDesc g, const Epi epi) {
;     ...
;     for (int kt = 0; kt < nk; ++kt) {
;       __syncthreads();
;       const u16* sA = sbase + (kt & 1) * STG;
;       const u16* sB = sA + BM * LS;
;       if (kt + 1 < nk) {
;         u16* nA = sbase + ((kt + 1) & 1) * STG;
; #pragma unroll
;         for (int j = 0; j < APT; ++j) *(u32x4*)(nA + (lr + RSTEP * j) * LS + lc * 8) = ra[j];
; #pragma unroll
;         for (int j = 0; j < BPT; ++j) *(u32x4*)(nA + BM * LS + (lr + RSTEP * j) * LS + lc * 8) = rb[j];
;         if (kt + 2 < nk) {
; #pragma unroll
;           for (int j = 0; j < APT; ++j) ra[j] = *(const u32x4*)(Ap + (size_t)j * RSTEP * g.lda + (kt + 2) * BK);
; #pragma unroll
;           for (int j = 0; j < BPT; ++j) rb[j] = *(const u32x4*)(Bp + (size_t)j * RSTEP * g.ldb + (kt + 2) * BK);
;         }
;       }
;       bf16x8 af[NKK][MF], bfr[NKK][2];
; #pragma unroll
;       for (int kk = 0; kk < NKK; ++kk) {
; #pragma unroll
;         for (int ni = 0; ni < 2; ++ni) bfr[kk][ni] = *(const bf16x8*)(sB + (wn * 64 + ni * 32 + l31) * LS + kk * 16 + h * 8);
; #pragma unroll
;         for (int mi = 0; mi < MF; ++mi) af[kk][mi] = *(const bf16x8*)(sA + (wm * (MF * 32) + mi * 32 + l31) * LS + kk * 16 + h * 8);
;       }
;       __builtin_amdgcn_sched_barrier(0);
; #pragma unroll
;       for (int kk = 0; kk < NKK; ++kk)
; #pragma unroll
;         for (int mi = 0; mi < MF; ++mi)
; #pragma unroll
;           for (int ni = 0; ni < 2; ++ni) acc[mi][ni] = MFMA32(bfr[kk][ni], af[kk][mi], acc[mi][ni]);
	s_waitcnt vmcnt(0)
	ds_write_b128 v54, v[78:81]
	ds_write_b128 v54, v[74:77] offset:4608
	ds_write_b128 v54, v[70:73] offset:9216
	ds_write_b128 v54, v[66:69] offset:13824
	ds_write_b128 v54, v[62:65] offset:18432
	ds_write_b128 v54, v[58:61] offset:23040
	global_load_dwordx4 v[58:61], v[50:51], off offset:640
	global_load_dwordx4 v[62:65], v[48:49], off offset:640
	global_load_dwordx4 v[66:69], v[46:47], off offset:640
	global_load_dwordx4 v[70:73], v[44:45], off offset:640
	global_load_dwordx4 v[74:77], v[42:43], off offset:640
	global_load_dwordx4 v[78:81], v[40:41], off offset:640
	v_mfma_f32_32x32x16_bf16 v[20:35], v[86:89], v[98:101], v[20:35]
	v_mfma_f32_32x32x16_bf16 v[4:19], v[82:85], v[98:101], v[4:19]
	v_mfma_f32_32x32x16_bf16 v[20:35], v[90:93], v[102:105], v[20:35]
	v_mfma_f32_32x32x16_bf16 v[4:19], v[94:97], v[102:105], v[4:19]
	v_mfma_f32_32x32x16_bf16 v[20:35], v[106:109], v[114:117], v[20:35]
	v_mfma_f32_32x32x16_bf16 v[4:19], v[110:113], v[114:117], v[4:19]
	v_mfma_f32_32x32x16_bf16 v[20:35], v[118:121], v[126:129], v[20:35]
	v_mfma_f32_32x32x16_bf16 v[4:19], v[122:125], v[126:129], v[4:19]
	ds_read_b128 v[82:85], v55 offset:41472
	ds_read_b128 v[86:89], v55 offset:36864
	ds_read_b128 v[90:93], v55 offset:36896
	ds_read_b128 v[94:97], v55 offset:41504
	ds_read_b128 v[98:101], v57 offset:27648
	ds_read_b128 v[102:105], v57 offset:27680
	ds_read_b128 v[106:109], v55 offset:36928
	ds_read_b128 v[110:113], v55 offset:41536
	ds_read_b128 v[114:117], v57 offset:27712
	ds_read_b128 v[118:121], v55 offset:36960
	ds_read_b128 v[122:125], v55 offset:41568
	ds_read_b128 v[126:129], v57 offset:27744
	s_waitcnt lgkmcnt(0)
	s_barrier
	s_waitcnt vmcnt(0)
	ds_write_b128 v54, v[78:81] offset:27648
	ds_write_b128 v54, v[74:77] offset:32256
	ds_write_b128 v54, v[70:73] offset:36864
	ds_write_b128 v54, v[66:69] offset:41472
	ds_write_b128 v54, v[62:65] offset:46080
	ds_write_b128 v54, v[58:61] offset:50688
	global_load_dwordx4 v[58:61], v[50:51], off offset:768
	global_load_dwordx4 v[62:65], v[48:49], off offset:768
	global_load_dwordx4 v[66:69], v[46:47], off offset:768
	global_load_dwordx4 v[70:73], v[44:45], off offset:768
	global_load_dwordx4 v[74:77], v[42:43], off offset:768
	global_load_dwordx4 v[78:81], v[40:41], off offset:768
	v_mfma_f32_32x32x16_bf16 v[20:35], v[86:89], v[98:101], v[20:35]
	v_mfma_f32_32x32x16_bf16 v[4:19], v[82:85], v[98:101], v[4:19]
	v_mfma_f32_32x32x16_bf16 v[20:35], v[90:93], v[102:105], v[20:35]
	v_mfma_f32_32x32x16_bf16 v[4:19], v[94:97], v[102:105], v[4:19]
	v_mfma_f32_32x32x16_bf16 v[20:35], v[106:109], v[114:117], v[20:35]
	v_mfma_f32_32x32x16_bf16 v[4:19], v[110:113], v[114:117], v[4:19]
	v_mfma_f32_32x32x16_bf16 v[20:35], v[118:121], v[126:129], v[20:35]
	v_mfma_f32_32x32x16_bf16 v[4:19], v[122:125], v[126:129], v[4:19]
	ds_read_b128 v[82:85], v55 offset:13824
	ds_read_b128 v[86:89], v55 offset:9216
	ds_read_b128 v[90:93], v55 offset:9248
	ds_read_b128 v[94:97], v55 offset:13856
	ds_read_b128 v[98:101], v57
	ds_read_b128 v[102:105], v57 offset:32
	ds_read_b128 v[106:109], v55 offset:9280
	ds_read_b128 v[110:113], v55 offset:13888
	ds_read_b128 v[114:117], v57 offset:64
	ds_read_b128 v[118:121], v55 offset:9312
	ds_read_b128 v[122:125], v55 offset:13920
	ds_read_b128 v[126:129], v57 offset:96
	s_waitcnt lgkmcnt(0)
	s_barrier
	s_waitcnt vmcnt(0)
	ds_write_b128 v54, v[78:81]
	ds_write_b128 v54, v[74:77] offset:4608
	ds_write_b128 v54, v[70:73] offset:9216
	ds_write_b128 v54, v[66:69] offset:13824
	ds_write_b128 v54, v[62:65] offset:18432
	ds_write_b128 v54, v[58:61] offset:23040
	global_load_dwordx4 v[58:61], v[50:51], off offset:896
	global_load_dwordx4 v[62:65], v[48:49], off offset:896
	global_load_dwordx4 v[66:69], v[46:47], off offset:896
	global_load_dwordx4 v[70:73], v[44:45], off offset:896
	global_load_dwordx4 v[74:77], v[42:43], off offset:896
	global_load_dwordx4 v[78:81], v[40:41], off offset:896
	v_mfma_f32_32x32x16_bf16 v[20:35], v[86:89], v[98:101], v[20:35]
	v_mfma_f32_32x32x16_bf16 v[4:19], v[82:85], v[98:101], v[4:19]
	v_mfma_f32_32x32x16_bf16 v[20:35], v[90:93], v[102:105], v[20:35]
	v_mfma_f32_32x32x16_bf16 v[4:19], v[94:97], v[102:105], v[4:19]
	v_mfma_f32_32x32x16_bf16 v[20:35], v[106:109], v[114:117], v[20:35]
	v_mfma_f32_32x32x16_bf16 v[4:19], v[110:113], v[114:117], v[4:19]
	v_mfma_f32_32x32x16_bf16 v[20:35], v[118:121], v[126:129], v[20:35]
	v_mfma_f32_32x32x16_bf16 v[4:19], v[122:125], v[126:129], v[4:19]
	ds_read_b128 v[82:85], v55 offset:41472
	ds_read_b128 v[86:89], v55 offset:36864
	ds_read_b128 v[90:93], v55 offset:36896
	ds_read_b128 v[94:97], v55 offset:41504
	ds_read_b128 v[98:101], v57 offset:27648
	ds_read_b128 v[102:105], v57 offset:27680
	ds_read_b128 v[106:109], v55 offset:36928
	ds_read_b128 v[110:113], v55 offset:41536
	ds_read_b128 v[114:117], v57 offset:27712
	ds_read_b128 v[118:121], v55 offset:36960
	ds_read_b128 v[122:125], v55 offset:41568
	ds_read_b128 v[126:129], v57 offset:27744
	s_waitcnt lgkmcnt(0)
	s_barrier
; #define MFMA32(a, b, c) __builtin_amdgcn_mfma_f32_32x32x16_bf16((a), (b), (c), 0, 0, 0)
; template <int MF, int BK, class Epi>
; DI void gemm_phase_t(char* lds, const GemmDesc g, const Epi epi) {
;     ...
;     for (int kt = 0; kt < nk; ++kt) {
;       __syncthreads();
;       const u16* sA = sbase + (kt & 1) * STG;
;       const u16* sB = sA + BM * LS;
;       if (kt + 1 < nk) {
;         u16* nA = sbase + ((kt + 1) & 1) * STG;
; #pragma unroll
;         for (int j = 0; j < APT; ++j) *(u32x4*)(nA + (lr + RSTEP * j) * LS + lc * 8) = ra[j];
; #pragma unroll
;         for (int j = 0; j < BPT; ++j) *(u32x4*)(nA + BM * LS + (lr + RSTEP * j) * LS + lc * 8) = rb[j];
;         if (kt + 2 < nk) {
; #pragma unroll
;           for (int j = 0; j < APT; ++j) ra[j] = *(const u32x4*)(Ap + (size_t)j * RSTEP * g.lda + (kt + 2) * BK);
; #pragma unroll
;           for (int j = 0; j < BPT; ++j) rb[j] = *(const u32x4*)(Bp + (size_t)j * RSTEP * g.ldb + (kt + 2) * BK);
;         }
;       }
;       bf16x8 af[NKK][MF], bfr[NKK][2];
; #pragma unroll
;       for (int kk = 0; kk < NKK; ++kk) {
; #pragma unroll
;         for (int ni = 0; ni < 2; ++ni) bfr[kk][ni] = *(const bf16x8*)(sB + (wn * 64 + ni * 32 + l31) * LS + kk * 16 + h * 8);
; #pragma unroll
;         for (int mi = 0; mi < MF; ++mi) af[kk][mi] = *(const bf16x8*)(sA + (wm * (MF * 32) + mi * 32 + l31) * LS + kk * 16 + h * 8);
;       }
;       __builtin_amdgcn_sched_barrier(0);
; #pragma unroll
;       for (int kk = 0; kk < NKK; ++kk)
; #pragma unroll
;         for (int mi = 0; mi < MF; ++mi)
; #pragma unroll
;           for (int ni = 0; ni < 2; ++ni) acc[mi][ni] = MFMA32(bfr[kk][ni], af[kk][mi], acc[mi][ni]);
	s_waitcnt vmcnt(0)
	ds_write_b128 v54, v[78:81] offset:27648
	ds_write_b128 v54, v[74:77] offset:32256
	ds_write_b128 v54, v[70:73] offset:36864
	ds_write_b128 v54, v[66:69] offset:41472
	ds_write_b128 v54, v[62:65] offset:46080
	ds_write_b128 v54, v[58:61] offset:50688
	global_load_dwordx4 v[58:61], v[50:51], off offset:1024
	global_load_dwordx4 v[62:65], v[48:49], off offset:1024
	global_load_dwordx4 v[66:69], v[46:47], off offset:1024
	global_load_dwordx4 v[70:73], v[44:45], off offset:1024
	global_load_dwordx4 v[74:77], v[42:43], off offset:1024
	global_load_dwordx4 v[78:81], v[40:41], off offset:1024
	v_mfma_f32_32x32x16_bf16 v[20:35], v[86:89], v[98:101], v[20:35]
	v_mfma_f32_32x32x16_bf16 v[4:19], v[82:85], v[98:101], v[4:19]
	v_mfma_f32_32x32x16_bf16 v[20:35], v[90:93], v[102:105], v[20:35]
	v_mfma_f32_32x32x16_bf16 v[4:19], v[94:97], v[102:105], v[4:19]
	v_mfma_f32_32x32x16_bf16 v[20:35], v[106:109], v[114:117], v[20:35]
	v_mfma_f32_32x32x16_bf16 v[4:19], v[110:113], v[114:117], v[4:19]
	v_mfma_f32_32x32x16_bf16 v[20:35], v[118:121], v[126:129], v[20:35]
	v_mfma_f32_32x32x16_bf16 v[4:19], v[122:125], v[126:129], v[4:19]
	ds_read_b128 v[82:85], v55 offset:13824
	ds_read_b128 v[86:89], v55 offset:9216
	ds_read_b128 v[90:93], v55 offset:9248
	ds_read_b128 v[94:97], v55 offset:13856
	ds_read_b128 v[98:101], v57
	ds_read_b128 v[102:105], v57 offset:32
	ds_read_b128 v[106:109], v55 offset:9280
	ds_read_b128 v[110:113], v55 offset:13888
	ds_read_b128 v[114:117], v57 offset:64
	ds_read_b128 v[118:121], v55 offset:9312
	ds_read_b128 v[122:125], v55 offset:13920
	ds_read_b128 v[126:129], v57 offset:96
	s_waitcnt lgkmcnt(0)
	s_barrier
	s_waitcnt vmcnt(0)
	ds_write_b128 v54, v[78:81]
	ds_write_b128 v54, v[74:77] offset:4608
	ds_write_b128 v54, v[70:73] offset:9216
	ds_write_b128 v54, v[66:69] offset:13824
	ds_write_b128 v54, v[62:65] offset:18432
	ds_write_b128 v54, v[58:61] offset:23040
	global_load_dwordx4 v[58:61], v[50:51], off offset:1152
	global_load_dwordx4 v[62:65], v[48:49], off offset:1152
	global_load_dwordx4 v[66:69], v[46:47], off offset:1152
	global_load_dwordx4 v[70:73], v[44:45], off offset:1152
	global_load_dwordx4 v[74:77], v[42:43], off offset:1152
	global_load_dwordx4 v[78:81], v[40:41], off offset:1152
	v_mfma_f32_32x32x16_bf16 v[20:35], v[86:89], v[98:101], v[20:35]
	v_mfma_f32_32x32x16_bf16 v[4:19], v[82:85], v[98:101], v[4:19]
	v_mfma_f32_32x32x16_bf16 v[20:35], v[90:93], v[102:105], v[20:35]
	v_mfma_f32_32x32x16_bf16 v[4:19], v[94:97], v[102:105], v[4:19]
	v_mfma_f32_32x32x16_bf16 v[20:35], v[106:109], v[114:117], v[20:35]
	v_mfma_f32_32x32x16_bf16 v[4:19], v[110:113], v[114:117], v[4:19]
	v_mfma_f32_32x32x16_bf16 v[20:35], v[118:121], v[126:129], v[20:35]
	v_mfma_f32_32x32x16_bf16 v[4:19], v[122:125], v[126:129], v[4:19]
	ds_read_b128 v[82:85], v55 offset:41472
	ds_read_b128 v[86:89], v55 offset:36864
	ds_read_b128 v[90:93], v55 offset:36896
	ds_read_b128 v[94:97], v55 offset:41504
	ds_read_b128 v[98:101], v57 offset:27648
	ds_read_b128 v[102:105], v57 offset:27680
	ds_read_b128 v[106:109], v55 offset:36928
	ds_read_b128 v[110:113], v55 offset:41536
	ds_read_b128 v[114:117], v57 offset:27712
	ds_read_b128 v[118:121], v55 offset:36960
	ds_read_b128 v[122:125], v55 offset:41568
	ds_read_b128 v[126:129], v57 offset:27744
	s_waitcnt lgkmcnt(0)
	s_barrier
	s_waitcnt vmcnt(0)
	ds_write_b128 v54, v[78:81] offset:27648
	ds_write_b128 v54, v[74:77] offset:32256
	ds_write_b128 v54, v[70:73] offset:36864
	ds_write_b128 v54, v[66:69] offset:41472
	ds_write_b128 v54, v[62:65] offset:46080
	ds_write_b128 v54, v[58:61] offset:50688
	global_load_dwordx4 v[58:61], v[50:51], off offset:1280
	global_load_dwordx4 v[62:65], v[48:49], off offset:1280
	global_load_dwordx4 v[66:69], v[46:47], off offset:1280
	global_load_dwordx4 v[70:73], v[44:45], off offset:1280
	global_load_dwordx4 v[74:77], v[42:43], off offset:1280
	global_load_dwordx4 v[78:81], v[40:41], off offset:1280
	v_mfma_f32_32x32x16_bf16 v[20:35], v[86:89], v[98:101], v[20:35]
	v_mfma_f32_32x32x16_bf16 v[4:19], v[82:85], v[98:101], v[4:19]
	v_mfma_f32_32x32x16_bf16 v[20:35], v[90:93], v[102:105], v[20:35]
	v_mfma_f32_32x32x16_bf16 v[4:19], v[94:97], v[102:105], v[4:19]
	v_mfma_f32_32x32x16_bf16 v[20:35], v[106:109], v[114:117], v[20:35]
	v_mfma_f32_32x32x16_bf16 v[4:19], v[110:113], v[114:117], v[4:19]
	v_mfma_f32_32x32x16_bf16 v[20:35], v[118:121], v[126:129], v[20:35]
	v_mfma_f32_32x32x16_bf16 v[4:19], v[122:125], v[126:129], v[4:19]
	ds_read_b128 v[82:85], v55 offset:13824
	ds_read_b128 v[86:89], v55 offset:9216
	ds_read_b128 v[90:93], v55 offset:9248
	ds_read_b128 v[94:97], v55 offset:13856
	ds_read_b128 v[98:101], v57
	ds_read_b128 v[102:105], v57 offset:32
	ds_read_b128 v[106:109], v55 offset:9280
	ds_read_b128 v[110:113], v55 offset:13888
	ds_read_b128 v[114:117], v57 offset:64
	ds_read_b128 v[118:121], v55 offset:9312
	ds_read_b128 v[122:125], v55 offset:13920
	ds_read_b128 v[126:129], v57 offset:96
	s_waitcnt lgkmcnt(0)
	s_barrier
; #define MFMA32(a, b, c) __builtin_amdgcn_mfma_f32_32x32x16_bf16((a), (b), (c), 0, 0, 0)
; template <int MF, int BK, class Epi>
; DI void gemm_phase_t(char* lds, const GemmDesc g, const Epi epi) {
;     ...
;     for (int kt = 0; kt < nk; ++kt) {
;       __syncthreads();
;       const u16* sA = sbase + (kt & 1) * STG;
;       const u16* sB = sA + BM * LS;
;       if (kt + 1 < nk) {
;         u16* nA = sbase + ((kt + 1) & 1) * STG;
; #pragma unroll
;         for (int j = 0; j < APT; ++j) *(u32x4*)(nA + (lr + RSTEP * j) * LS + lc * 8) = ra[j];
; #pragma unroll
;         for (int j = 0; j < BPT; ++j) *(u32x4*)(nA + BM * LS + (lr + RSTEP * j) * LS + lc * 8) = rb[j];
;         if (kt + 2 < nk) {
; #pragma unroll
;           for (int j = 0; j < APT; ++j) ra[j] = *(const u32x4*)(Ap + (size_t)j * RSTEP * g.lda + (kt + 2) * BK);
; #pragma unroll
;           for (int j = 0; j < BPT; ++j) rb[j] = *(const u32x4*)(Bp + (size_t)j * RSTEP * g.ldb + (kt + 2) * BK);
;         }
;       }
;       bf16x8 af[NKK][MF], bfr[NKK][2];
; #pragma unroll
;       for (int kk = 0; kk < NKK; ++kk) {
; #pragma unroll
;         for (int ni = 0; ni < 2; ++ni) bfr[kk][ni] = *(const bf16x8*)(sB + (wn * 64 + ni * 32 + l31) * LS + kk * 16 + h * 8);
; #pragma unroll
;         for (int mi = 0; mi < MF; ++mi) af[kk][mi] = *(const bf16x8*)(sA + (wm * (MF * 32) + mi * 32 + l31) * LS + kk * 16 + h * 8);
;       }
;       __builtin_amdgcn_sched_barrier(0);
; #pragma unroll
;       for (int kk = 0; kk < NKK; ++kk)
; #pragma unroll
;         for (int mi = 0; mi < MF; ++mi)
; #pragma unroll
;           for (int ni = 0; ni < 2; ++ni) acc[mi][ni] = MFMA32(bfr[kk][ni], af[kk][mi], acc[mi][ni]);
	s_waitcnt vmcnt(0)
	ds_write_b128 v54, v[78:81]
	ds_write_b128 v54, v[74:77] offset:4608
	ds_write_b128 v54, v[70:73] offset:9216
	ds_write_b128 v54, v[66:69] offset:13824
	ds_write_b128 v54, v[62:65] offset:18432
	ds_write_b128 v54, v[58:61] offset:23040
	global_load_dwordx4 v[58:61], v[50:51], off offset:1408
	global_load_dwordx4 v[62:65], v[48:49], off offset:1408
	global_load_dwordx4 v[66:69], v[46:47], off offset:1408
	global_load_dwordx4 v[70:73], v[44:45], off offset:1408
	global_load_dwordx4 v[74:77], v[42:43], off offset:1408
	global_load_dwordx4 v[78:81], v[40:41], off offset:1408
	v_mfma_f32_32x32x16_bf16 v[20:35], v[86:89], v[98:101], v[20:35]
	v_mfma_f32_32x32x16_bf16 v[4:19], v[82:85], v[98:101], v[4:19]
	v_mfma_f32_32x32x16_bf16 v[20:35], v[90:93], v[102:105], v[20:35]
	v_mfma_f32_32x32x16_bf16 v[4:19], v[94:97], v[102:105], v[4:19]
	v_mfma_f32_32x32x16_bf16 v[20:35], v[106:109], v[114:117], v[20:35]
	v_mfma_f32_32x32x16_bf16 v[4:19], v[110:113], v[114:117], v[4:19]
	v_mfma_f32_32x32x16_bf16 v[20:35], v[118:121], v[126:129], v[20:35]
	v_mfma_f32_32x32x16_bf16 v[4:19], v[122:125], v[126:129], v[4:19]
	ds_read_b128 v[82:85], v55 offset:41472
	ds_read_b128 v[86:89], v55 offset:36864
	ds_read_b128 v[90:93], v55 offset:36896
	ds_read_b128 v[94:97], v55 offset:41504
	ds_read_b128 v[98:101], v57 offset:27648
	ds_read_b128 v[102:105], v57 offset:27680
	ds_read_b128 v[106:109], v55 offset:36928
	ds_read_b128 v[110:113], v55 offset:41536
	ds_read_b128 v[114:117], v57 offset:27712
	ds_read_b128 v[118:121], v55 offset:36960
	ds_read_b128 v[122:125], v55 offset:41568
	ds_read_b128 v[126:129], v57 offset:27744
	s_waitcnt lgkmcnt(0)
	s_barrier
	s_waitcnt vmcnt(0)
	ds_write_b128 v54, v[78:81] offset:27648
	ds_write_b128 v54, v[74:77] offset:32256
	ds_write_b128 v54, v[70:73] offset:36864
	ds_write_b128 v54, v[66:69] offset:41472
	ds_write_b128 v54, v[62:65] offset:46080
	ds_write_b128 v54, v[58:61] offset:50688
	global_load_dwordx4 v[58:61], v[50:51], off offset:1536
	global_load_dwordx4 v[62:65], v[48:49], off offset:1536
	global_load_dwordx4 v[66:69], v[46:47], off offset:1536
	global_load_dwordx4 v[70:73], v[44:45], off offset:1536
	global_load_dwordx4 v[74:77], v[42:43], off offset:1536
	global_load_dwordx4 v[78:81], v[40:41], off offset:1536
	v_mfma_f32_32x32x16_bf16 v[20:35], v[86:89], v[98:101], v[20:35]
	v_mfma_f32_32x32x16_bf16 v[4:19], v[82:85], v[98:101], v[4:19]
	v_mfma_f32_32x32x16_bf16 v[20:35], v[90:93], v[102:105], v[20:35]
	v_mfma_f32_32x32x16_bf16 v[4:19], v[94:97], v[102:105], v[4:19]
	v_mfma_f32_32x32x16_bf16 v[20:35], v[106:109], v[114:117], v[20:35]
	v_mfma_f32_32x32x16_bf16 v[4:19], v[110:113], v[114:117], v[4:19]
	v_mfma_f32_32x32x16_bf16 v[20:35], v[118:121], v[126:129], v[20:35]
	v_mfma_f32_32x32x16_bf16 v[4:19], v[122:125], v[126:129], v[4:19]
	ds_read_b128 v[82:85], v55 offset:13824
	ds_read_b128 v[86:89], v55 offset:9216
	ds_read_b128 v[90:93], v55 offset:9248
	ds_read_b128 v[94:97], v55 offset:13856
	ds_read_b128 v[98:101], v57
	ds_read_b128 v[102:105], v57 offset:32
	ds_read_b128 v[106:109], v55 offset:9280
	ds_read_b128 v[110:113], v55 offset:13888
	ds_read_b128 v[114:117], v57 offset:64
	ds_read_b128 v[118:121], v55 offset:9312
	ds_read_b128 v[122:125], v55 offset:13920
	ds_read_b128 v[126:129], v57 offset:96
	s_waitcnt lgkmcnt(0)
	s_barrier
	s_waitcnt vmcnt(0)
	ds_write_b128 v54, v[78:81]
	ds_write_b128 v54, v[74:77] offset:4608
	ds_write_b128 v54, v[70:73] offset:9216
	ds_write_b128 v54, v[66:69] offset:13824
	ds_write_b128 v54, v[62:65] offset:18432
	ds_write_b128 v54, v[58:61] offset:23040
	global_load_dwordx4 v[58:61], v[50:51], off offset:1664
	global_load_dwordx4 v[62:65], v[48:49], off offset:1664
	global_load_dwordx4 v[66:69], v[46:47], off offset:1664
	global_load_dwordx4 v[70:73], v[44:45], off offset:1664
	global_load_dwordx4 v[74:77], v[42:43], off offset:1664
	global_load_dwordx4 v[78:81], v[40:41], off offset:1664
	v_mfma_f32_32x32x16_bf16 v[20:35], v[86:89], v[98:101], v[20:35]
	v_mfma_f32_32x32x16_bf16 v[4:19], v[82:85], v[98:101], v[4:19]
	v_mfma_f32_32x32x16_bf16 v[20:35], v[90:93], v[102:105], v[20:35]
	v_mfma_f32_32x32x16_bf16 v[4:19], v[94:97], v[102:105], v[4:19]
	v_mfma_f32_32x32x16_bf16 v[20:35], v[106:109], v[114:117], v[20:35]
	v_mfma_f32_32x32x16_bf16 v[4:19], v[110:113], v[114:117], v[4:19]
	v_mfma_f32_32x32x16_bf16 v[20:35], v[118:121], v[126:129], v[20:35]
	v_mfma_f32_32x32x16_bf16 v[4:19], v[122:125], v[126:129], v[4:19]
	ds_read_b128 v[82:85], v55 offset:41472
	ds_read_b128 v[86:89], v55 offset:36864
	ds_read_b128 v[90:93], v55 offset:36896
	ds_read_b128 v[94:97], v55 offset:41504
	ds_read_b128 v[98:101], v57 offset:27648
	ds_read_b128 v[102:105], v57 offset:27680
	ds_read_b128 v[106:109], v55 offset:36928
	ds_read_b128 v[110:113], v55 offset:41536
	ds_read_b128 v[114:117], v57 offset:27712
	ds_read_b128 v[118:121], v55 offset:36960
	ds_read_b128 v[122:125], v55 offset:41568
	ds_read_b128 v[126:129], v57 offset:27744
	s_waitcnt lgkmcnt(0)
	s_barrier
; #define MFMA32(a, b, c) __builtin_amdgcn_mfma_f32_32x32x16_bf16((a), (b), (c), 0, 0, 0)
; template <int MF, int BK, class Epi>
; DI void gemm_phase_t(char* lds, const GemmDesc g, const Epi epi) {
;     ...
;     for (int kt = 0; kt < nk; ++kt) {
;       __syncthreads();
;       const u16* sA = sbase + (kt & 1) * STG;
;       const u16* sB = sA + BM * LS;
;       if (kt + 1 < nk) {
;         u16* nA = sbase + ((kt + 1) & 1) * STG;
; #pragma unroll
;         for (int j = 0; j < APT; ++j) *(u32x4*)(nA + (lr + RSTEP * j) * LS + lc * 8) = ra[j];
; #pragma unroll
;         for (int j = 0; j < BPT; ++j) *(u32x4*)(nA + BM * LS + (lr + RSTEP * j) * LS + lc * 8) = rb[j];
;         if (kt + 2 < nk) {
; #pragma unroll
;           for (int j = 0; j < APT; ++j) ra[j] = *(const u32x4*)(Ap + (size_t)j * RSTEP * g.lda + (kt + 2) * BK);
; #pragma unroll
;           for (int j = 0; j < BPT; ++j) rb[j] = *(const u32x4*)(Bp + (size_t)j * RSTEP * g.ldb + (kt + 2) * BK);
;         }
;       }
;       bf16x8 af[NKK][MF], bfr[NKK][2];
; #pragma unroll
;       for (int kk = 0; kk < NKK; ++kk) {
; #pragma unroll
;         for (int ni = 0; ni < 2; ++ni) bfr[kk][ni] = *(const bf16x8*)(sB + (wn * 64 + ni * 32 + l31) * LS + kk * 16 + h * 8);
; #pragma unroll
;         for (int mi = 0; mi < MF; ++mi) af[kk][mi] = *(const bf16x8*)(sA + (wm * (MF * 32) + mi * 32 + l31) * LS + kk * 16 + h * 8);
;       }
;       __builtin_amdgcn_sched_barrier(0);
; #pragma unroll
;       for (int kk = 0; kk < NKK; ++kk)
; #pragma unroll
;         for (int mi = 0; mi < MF; ++mi)
; #pragma unroll
;           for (int ni = 0; ni < 2; ++ni) acc[mi][ni] = MFMA32(bfr[kk][ni], af[kk][mi], acc[mi][ni]);
	s_waitcnt vmcnt(0)
	ds_write_b128 v54, v[78:81] offset:27648
	ds_write_b128 v54, v[74:77] offset:32256
	ds_write_b128 v54, v[70:73] offset:36864
	ds_write_b128 v54, v[66:69] offset:41472
	ds_write_b128 v54, v[62:65] offset:46080
	ds_write_b128 v54, v[58:61] offset:50688
	global_load_dwordx4 v[58:61], v[50:51], off offset:1792
	global_load_dwordx4 v[62:65], v[48:49], off offset:1792
	global_load_dwordx4 v[66:69], v[46:47], off offset:1792
	global_load_dwordx4 v[70:73], v[44:45], off offset:1792
	global_load_dwordx4 v[74:77], v[42:43], off offset:1792
	global_load_dwordx4 v[78:81], v[40:41], off offset:1792
	v_mfma_f32_32x32x16_bf16 v[20:35], v[86:89], v[98:101], v[20:35]
	v_mfma_f32_32x32x16_bf16 v[4:19], v[82:85], v[98:101], v[4:19]
	v_mfma_f32_32x32x16_bf16 v[20:35], v[90:93], v[102:105], v[20:35]
	v_mfma_f32_32x32x16_bf16 v[4:19], v[94:97], v[102:105], v[4:19]
	v_mfma_f32_32x32x16_bf16 v[20:35], v[106:109], v[114:117], v[20:35]
	v_mfma_f32_32x32x16_bf16 v[4:19], v[110:113], v[114:117], v[4:19]
	v_mfma_f32_32x32x16_bf16 v[20:35], v[118:121], v[126:129], v[20:35]
	v_mfma_f32_32x32x16_bf16 v[4:19], v[122:125], v[126:129], v[4:19]
	ds_read_b128 v[82:85], v55 offset:13824
	ds_read_b128 v[86:89], v55 offset:9216
	ds_read_b128 v[90:93], v55 offset:9248
	ds_read_b128 v[94:97], v55 offset:13856
	ds_read_b128 v[98:101], v57
	ds_read_b128 v[102:105], v57 offset:32
	ds_read_b128 v[106:109], v55 offset:9280
	ds_read_b128 v[110:113], v55 offset:13888
	ds_read_b128 v[114:117], v57 offset:64
	ds_read_b128 v[118:121], v55 offset:9312
	ds_read_b128 v[122:125], v55 offset:13920
	ds_read_b128 v[126:129], v57 offset:96
	s_waitcnt lgkmcnt(7)
	v_mfma_f32_32x32x16_bf16 v[20:35], v[86:89], v[98:101], v[20:35]
	s_waitcnt lgkmcnt(0)
	s_barrier
	v_mfma_f32_32x32x16_bf16 v[4:19], v[82:85], v[98:101], v[4:19]
	global_load_dwordx4 v[82:85], v[50:51], off offset:1920
	s_nop 0
	global_load_dwordx4 v[48:51], v[48:49], off offset:1920
	v_mfma_f32_32x32x16_bf16 v[20:35], v[90:93], v[102:105], v[20:35]
	global_load_dwordx4 v[86:89], v[46:47], off offset:1920
	s_nop 0
	global_load_dwordx4 v[44:47], v[44:45], off offset:1920
	s_nop 0
	global_load_dwordx4 v[90:93], v[42:43], off offset:1920
	s_nop 0
	global_load_dwordx4 v[40:43], v[40:41], off offset:1920
	s_waitcnt vmcnt(6)
	ds_write_b128 v54, v[78:81]
	ds_write_b128 v54, v[74:77] offset:4608
	ds_write_b128 v54, v[70:73] offset:9216
	ds_write_b128 v54, v[66:69] offset:13824
	ds_write_b128 v54, v[62:65] offset:18432
	ds_write_b128 v54, v[58:61] offset:23040
	ds_read_b128 v[58:61], v55 offset:36864
	ds_read_b128 v[62:65], v55 offset:36896
	ds_read_b128 v[66:69], v55 offset:41472
	ds_read_b128 v[70:73], v55 offset:41504
	v_mfma_f32_32x32x16_bf16 v[4:19], v[94:97], v[102:105], v[4:19]
	v_mfma_f32_32x32x16_bf16 v[20:35], v[106:109], v[114:117], v[20:35]
	v_mfma_f32_32x32x16_bf16 v[4:19], v[110:113], v[114:117], v[4:19]
	ds_read_b128 v[74:77], v57 offset:27648
	ds_read_b128 v[78:81], v57 offset:27680
	ds_read_b128 v[94:97], v55 offset:36928
	ds_read_b128 v[98:101], v55 offset:36960
	ds_read_b128 v[102:105], v55 offset:41536
	ds_read_b128 v[106:109], v55 offset:41568
	ds_read_b128 v[110:113], v57 offset:27712
	ds_read_b128 v[114:117], v57 offset:27744
	v_mfma_f32_32x32x16_bf16 v[20:35], v[118:121], v[126:129], v[20:35]
	v_mfma_f32_32x32x16_bf16 v[4:19], v[122:125], v[126:129], v[4:19]
	s_waitcnt lgkmcnt(7)
	v_mfma_f32_32x32x16_bf16 v[20:35], v[58:61], v[74:77], v[20:35]
	s_waitcnt lgkmcnt(0)
	s_barrier
	s_waitcnt vmcnt(0)
	ds_write_b128 v54, v[40:43] offset:27648
	ds_write_b128 v54, v[90:93] offset:32256
	ds_write_b128 v54, v[44:47] offset:36864
	ds_write_b128 v54, v[86:89] offset:41472
	ds_write_b128 v54, v[48:51] offset:46080
	ds_write_b128 v54, v[82:85] offset:50688
	ds_read_b128 v[40:43], v55 offset:9216
	ds_read_b128 v[44:47], v55 offset:9248
	ds_read_b128 v[48:51], v55 offset:13824
	ds_read_b128 v[58:61], v55 offset:13856
	v_mfma_f32_32x32x16_bf16 v[4:19], v[66:69], v[74:77], v[4:19]
	v_mfma_f32_32x32x16_bf16 v[20:35], v[62:65], v[78:81], v[20:35]
	v_mfma_f32_32x32x16_bf16 v[4:19], v[70:73], v[78:81], v[4:19]
	ds_read_b128 v[62:65], v57
	ds_read_b128 v[66:69], v57 offset:32
	ds_read_b128 v[70:73], v55 offset:9280
	ds_read_b128 v[74:77], v55 offset:9312
	ds_read_b128 v[78:81], v55 offset:13888
	ds_read_b128 v[82:85], v55 offset:13920
	ds_read_b128 v[86:89], v57 offset:64
	ds_read_b128 v[90:93], v57 offset:96
	v_mfma_f32_32x32x16_bf16 v[20:35], v[94:97], v[110:113], v[20:35]
	v_mfma_f32_32x32x16_bf16 v[4:19], v[102:105], v[110:113], v[4:19]
	v_mfma_f32_32x32x16_bf16 v[20:35], v[98:101], v[114:117], v[20:35]
	v_mfma_f32_32x32x16_bf16 v[4:19], v[106:109], v[114:117], v[4:19]
	s_waitcnt lgkmcnt(7)
	v_mfma_f32_32x32x16_bf16 v[20:35], v[40:43], v[62:65], v[20:35]
	s_waitcnt lgkmcnt(0)
	s_barrier
; #define MFMA32(a, b, c) __builtin_amdgcn_mfma_f32_32x32x16_bf16((a), (b), (c), 0, 0, 0)
; template <int MF, int BK, class Epi>
; DI void gemm_phase_t(char* lds, const GemmDesc g, const Epi epi) {
;     ...
;       for (int kk = 0; kk < NKK; ++kk)
; #pragma unroll
;         for (int mi = 0; mi < MF; ++mi)
; #pragma unroll
;           for (int ni = 0; ni < 2; ++ni) acc[mi][ni] = MFMA32(bfr[kk][ni], af[kk][mi], acc[mi][ni]);
;     }
;     epi(acc, g.mbase + m0 + wm * (MF * 32), n0 + wn * 64, l31, h);
;   template <int MF> DI void operator()(f32x16 (&acc)[MF][2], int mb, int nb, int l31, int h) const {
; #pragma unroll
;     for (int mi = 0; mi < MF; ++mi) {
;       const int row = mb + mi * 32 + l31;
;       const float* gr = gate + (size_t)modrow(row) * 6144;
;       const float* rp = row < TL ? res_lat + (size_t)row * D : res_ctx + (size_t)(row - TL) * D;
;       float* op = row < TL ? out_lat + (size_t)row * D : out_ctx + (size_t)(row - TL) * D;
; #pragma unroll
;       for (int g4 = 0; g4 < 4; ++g4)
; #pragma unroll
;         for (int ni = 0; ni < 2; ++ni) {
;           const int col0 = nb + 16 * g4 + 8 * h + 4 * ni;
;           const float4 gt = *(const float4*)(gr + col0);
;           const float4 rv = *(const float4*)(rp + col0);
;           *(float4*)(op + col0) = make_float4(rv.x + gt.x * acc[mi][ni][4 * g4], rv.y + gt.y * acc[mi][ni][4 * g4 + 1], rv.z + gt.z * acc[mi][ni][4 * g4 + 2], rv.w + gt.w * acc[mi][ni][4 * g4 + 3]);
;         }
;     }
	v_mfma_f32_32x32x16_bf16 v[4:19], v[48:51], v[62:65], v[4:19]
	v_mfma_f32_32x32x16_bf16 v[20:35], v[44:47], v[66:69], v[20:35]
	v_mfma_f32_32x32x16_bf16 v[4:19], v[58:61], v[66:69], v[4:19]
	v_mfma_f32_32x32x16_bf16 v[20:35], v[70:73], v[86:89], v[20:35]
	v_mfma_f32_32x32x16_bf16 v[4:19], v[78:81], v[86:89], v[4:19]
	v_mfma_f32_32x32x16_bf16 v[20:35], v[74:77], v[90:93], v[20:35]
	v_mfma_f32_32x32x16_bf16 v[4:19], v[82:85], v[90:93], v[4:19]
	ds_read_b128 v[40:43], v55 offset:41472
	ds_read_b128 v[44:47], v55 offset:36864
	ds_read_b128 v[48:51], v55 offset:36896
	ds_read_b128 v[58:61], v55 offset:41504
	ds_read_b128 v[62:65], v57 offset:27648
	ds_read_b128 v[66:69], v57 offset:27680
	ds_read_b128 v[70:73], v55 offset:36928
	ds_read_b128 v[74:77], v55 offset:41536
	ds_read_b128 v[78:81], v57 offset:27712
	ds_read_b128 v[82:85], v55 offset:36960
	ds_read_b128 v[86:89], v55 offset:41568
	ds_read_b128 v[90:93], v57 offset:27744
	s_waitcnt lgkmcnt(7)
	v_mfma_f32_32x32x16_bf16 v[20:35], v[44:47], v[62:65], v[20:35]
	v_add_u32_e32 v44, s4, v56
	v_ashrrev_i32_e32 v45, 31, v44
	s_add_i32 s6, s6, s8
	s_add_i32 s2, s2, s3
	s_cmpk_lt_i32 s6, 0x100
	v_mfma_f32_32x32x16_bf16 v[4:19], v[40:43], v[62:65], v[4:19]
	v_add_u32_e32 v40, s5, v53
	v_min_i32_e32 v2, 0x8000, v40
	v_ashrrev_i32_e32 v2, 12, v2
	v_mul_hi_i32_i24_e32 v43, 0x6000, v2
	v_mul_i32_i24_e32 v42, 0x6000, v2
	v_add_u32_e32 v2, 0xffff8000, v40
	v_ashrrev_i32_e32 v41, 31, v40
	s_waitcnt lgkmcnt(6)
	v_mfma_f32_32x32x16_bf16 v[20:35], v[48:51], v[66:69], v[20:35]
	v_lshlrev_b64 v[48:49], 12, v[2:3]
	v_lshlrev_b64 v[50:51], 12, v[40:41]
	v_lshl_add_u64 v[46:47], s[14:15], 0, v[50:51]
	v_cmp_gt_i32_e32 vcc, s7, v40
	v_lshl_add_u64 v[42:43], s[0:1], 0, v[42:43]
	v_lshl_add_u64 v[50:51], s[28:29], 0, v[50:51]
	v_mfma_f32_32x32x16_bf16 v[4:19], v[58:61], v[66:69], v[4:19]
	v_lshl_add_u64 v[58:59], s[12:13], 0, v[48:49]
	v_cndmask_b32_e32 v41, v59, v47, vcc
	v_cndmask_b32_e32 v40, v58, v46, vcc
	v_lshlrev_b64 v[58:59], 2, v[44:45]
	v_lshl_add_u64 v[60:61], v[42:43], 0, v[58:59]
	v_lshl_add_u64 v[62:63], v[40:41], 0, v[58:59]
	s_waitcnt lgkmcnt(3)
	v_mfma_f32_32x32x16_bf16 v[20:35], v[70:73], v[78:81], v[20:35]
	v_lshl_add_u64 v[48:49], s[30:31], 0, v[48:49]
	v_cndmask_b32_e32 v49, v49, v51, vcc
	v_cndmask_b32_e32 v48, v48, v50, vcc
	v_lshl_add_u64 v[48:49], v[48:49], 0, v[58:59]
	s_waitcnt lgkmcnt(0)
	v_mfma_f32_32x32x16_bf16 v[20:35], v[82:85], v[90:93], v[20:35]
	v_mfma_f32_32x32x16_bf16 v[4:19], v[74:77], v[78:81], v[4:19]
	v_mfma_f32_32x32x16_bf16 v[4:19], v[86:89], v[90:93], v[4:19]
	global_load_dwordx4 v[118:121], v[60:61], off
	global_load_dwordx4 v[150:153], v[62:63], off
	global_load_dwordx4 v[122:125], v[60:61], off offset:16
	global_load_dwordx4 v[154:157], v[62:63], off offset:16
	global_load_dwordx4 v[126:129], v[60:61], off offset:64
	global_load_dwordx4 v[158:161], v[62:63], off offset:64
	global_load_dwordx4 v[130:133], v[60:61], off offset:80
	global_load_dwordx4 v[162:165], v[62:63], off offset:80
	global_load_dwordx4 v[134:137], v[60:61], off offset:128
	global_load_dwordx4 v[168:171], v[62:63], off offset:128
	global_load_dwordx4 v[138:141], v[60:61], off offset:144
	global_load_dwordx4 v[172:175], v[62:63], off offset:144
	global_load_dwordx4 v[142:145], v[60:61], off offset:192
	global_load_dwordx4 v[176:179], v[62:63], off offset:192
	global_load_dwordx4 v[146:149], v[60:61], off offset:208
	global_load_dwordx4 v[180:183], v[62:63], off offset:208
	s_waitcnt vmcnt(0)
	s_nop 4
	v_fma_f32 v20, v20, v118, v150
	v_fma_f32 v21, v21, v119, v151
	v_fma_f32 v22, v22, v120, v152
	v_fma_f32 v23, v23, v121, v153
	global_store_dwordx4 v[48:49], v[20:23], off
	v_fma_f32 v4, v4, v122, v154
	v_fma_f32 v5, v5, v123, v155
	v_fma_f32 v6, v6, v124, v156
	v_fma_f32 v7, v7, v125, v157
	global_store_dwordx4 v[48:49], v[4:7], off offset:16
	v_fma_f32 v24, v24, v126, v158
	v_fma_f32 v25, v25, v127, v159
	v_fma_f32 v26, v26, v128, v160
	v_fma_f32 v27, v27, v129, v161
	global_store_dwordx4 v[48:49], v[24:27], off offset:64
	v_fma_f32 v8, v8, v130, v162
	v_fma_f32 v9, v9, v131, v163
	v_fma_f32 v10, v10, v132, v164
	v_fma_f32 v11, v11, v133, v165
	global_store_dwordx4 v[48:49], v[8:11], off offset:80
	v_fma_f32 v28, v28, v134, v168
	v_fma_f32 v29, v29, v135, v169
	v_fma_f32 v30, v30, v136, v170
	v_fma_f32 v31, v31, v137, v171
	global_store_dwordx4 v[48:49], v[28:31], off offset:128
	v_fma_f32 v12, v12, v138, v172
	v_fma_f32 v13, v13, v139, v173
	v_fma_f32 v14, v14, v140, v174
	v_fma_f32 v15, v15, v141, v175
	global_store_dwordx4 v[48:49], v[12:15], off offset:144
	v_fma_f32 v32, v32, v142, v176
	v_fma_f32 v33, v33, v143, v177
	v_fma_f32 v34, v34, v144, v178
	v_fma_f32 v35, v35, v145, v179
	global_store_dwordx4 v[48:49], v[32:35], off offset:192
	v_fma_f32 v16, v16, v146, v180
	v_fma_f32 v17, v17, v147, v181
	v_fma_f32 v18, v18, v148, v182
	v_fma_f32 v19, v19, v149, v183
	global_store_dwordx4 v[48:49], v[16:19], off offset:208
	s_cbranch_scc1 .LBB0_311
